# attention rings: the next LDS-DMA piece of a half-step is issued behind its MFMAs (MFMA shadow) instead of in front of the fragment reads; on top of v34
# baseline (speedup 1.0000x reference)
; template <bool LOCAL>
; __device__ __forceinline__ void attn_unit(const bf16_t* Q, const bf16_t* KT, const bf16_t* VT, bf16_t* O, LAS unsigned char* lds, int b, int h, int r, int w, int tq, int lane) {
;     ...
;     float mx = -INFINITY;
; #pragma unroll
;     for (int i = 0; i < 2 * NP; ++i) mx = fmaxf(mx, fmaxf(fmaxf(s[i][0], s[i][1]), fmaxf(s[i][2], s[i][3])));
;     mx = fmaxf(mx, __shfl_xor(mx, 16)); mx = fmaxf(mx, __shfl_xor(mx, 32));
.LBB9_673:
	s_or_b64 exec, exec, s[34:35]
	v_max_f32_e32 v66, v126, v126
	v_max_f32_e32 v67, v134, v134
	v_max_f32_e32 v66, v67, v66
	v_max_f32_e32 v67, v123, v123
	v_max_f32_e32 v68, v129, v129
	v_max_f32_e32 v67, v68, v67
	v_max3_f32 v66, v133, v132, v66
	v_max3_f32 v67, v128, v127, v67
	v_max3_f32 v66, v66, s16, v67
	v_max_f32_e32 v67, v118, v118
	v_max_f32_e32 v68, v125, v125
	v_max_f32_e32 v67, v68, v67
	v_max_f32_e32 v68, v115, v115
	v_max_f32_e32 v69, v121, v121
	v_max_f32_e32 v68, v69, v68
	v_max3_f32 v67, v124, v122, v67
	v_max3_f32 v68, v120, v119, v68
	v_max3_f32 v66, v66, v67, v68
	v_max_f32_e32 v67, v110, v110
	v_max_f32_e32 v68, v117, v117
	v_max_f32_e32 v67, v68, v67
	v_max_f32_e32 v68, v113, v113
	v_max_f32_e32 v69, v135, v135
	v_max_f32_e32 v68, v69, v68
	v_max3_f32 v67, v116, v114, v67
	v_max3_f32 v68, v112, v111, v68
	v_max3_f32 v66, v66, v67, v68
	v_max_f32_e32 v67, v102, v102
	v_max_f32_e32 v68, v109, v109
	v_max_f32_e32 v67, v68, v67
	v_max_f32_e32 v68, v99, v99
	v_max_f32_e32 v69, v105, v105
	v_max_f32_e32 v68, v69, v68
	v_max3_f32 v67, v108, v107, v67
	v_max3_f32 v68, v104, v103, v68
	v_max3_f32 v66, v66, v67, v68
	v_max_f32_e32 v67, v94, v94
	v_max_f32_e32 v68, v101, v101
	v_max_f32_e32 v67, v68, v67
	v_max_f32_e32 v68, v91, v91
	v_max_f32_e32 v69, v97, v97
	v_max_f32_e32 v68, v69, v68
	v_max3_f32 v67, v100, v98, v67
	v_max3_f32 v68, v96, v95, v68
	v_max3_f32 v66, v66, v67, v68
	v_max_f32_e32 v67, v86, v86
	v_max_f32_e32 v68, v93, v93
	v_max_f32_e32 v67, v68, v67
	v_max_f32_e32 v68, v89, v89
	v_max_f32_e32 v69, v138, v138
	v_max_f32_e32 v68, v69, v68
	v_max3_f32 v67, v92, v90, v67
	v_max3_f32 v68, v88, v87, v68
	v_max3_f32 v66, v66, v67, v68
	v_max_f32_e32 v67, v139, v139
	v_max_f32_e32 v68, v141, v141
	v_max_f32_e32 v67, v68, v67
	v_max_f32_e32 v68, v197, v197
	v_max_f32_e32 v69, v199, v199
	v_max_f32_e32 v68, v69, v68
	v_max3_f32 v67, v137, v136, v67
	v_max3_f32 v68, v195, v140, v68
	v_max3_f32 v66, v66, v67, v68
	v_max_f32_e32 v67, v200, v200
	v_max_f32_e32 v68, v202, v202
	v_max_f32_e32 v67, v68, v67
	v_max_f32_e32 v68, v204, v204
	v_max_f32_e32 v69, v205, v205
	v_max_f32_e32 v68, v69, v68
	v_max3_f32 v67, v198, v196, v67
	v_max3_f32 v68, v203, v201, v68
	v_max3_f32 v66, v66, v67, v68
	v_max_f32_e32 v67, v5, v5
	v_max_f32_e32 v68, v4, v4
	v_max_f32_e32 v67, v68, v67
	v_max_f32_e32 v68, v13, v13
	v_max_f32_e32 v69, v12, v12
	v_max_f32_e32 v68, v69, v68
	v_max3_f32 v67, v2, v3, v67
	v_max3_f32 v68, v10, v11, v68
	v_max3_f32 v66, v66, v67, v68
	v_max_f32_e32 v67, v9, v9
	v_max_f32_e32 v68, v8, v8
	v_max_f32_e32 v67, v68, v67
	v_max_f32_e32 v68, v21, v21
	v_max_f32_e32 v69, v20, v20
	v_max_f32_e32 v68, v69, v68
	v_max3_f32 v67, v6, v7, v67
	v_max3_f32 v68, v18, v19, v68
	v_max3_f32 v66, v66, v67, v68
	v_max_f32_e32 v67, v17, v17
	v_max_f32_e32 v68, v16, v16
	v_max_f32_e32 v67, v68, v67
	v_max_f32_e32 v68, v29, v29
	v_max_f32_e32 v69, v28, v28
	v_max_f32_e32 v68, v69, v68
	v_max3_f32 v67, v14, v15, v67
	v_max3_f32 v68, v26, v27, v68
	v_max3_f32 v66, v66, v67, v68
	v_max_f32_e32 v67, v25, v25
	v_max_f32_e32 v68, v24, v24
	v_max_f32_e32 v67, v68, v67
	v_max_f32_e32 v68, v37, v37
	v_max_f32_e32 v69, v36, v36
	v_max_f32_e32 v68, v69, v68
	v_max3_f32 v67, v22, v23, v67
	v_max3_f32 v68, v34, v35, v68
	v_max3_f32 v66, v66, v67, v68
	v_max_f32_e32 v67, v33, v33
	v_max_f32_e32 v68, v32, v32
	v_max_f32_e32 v67, v68, v67
	v_max_f32_e32 v68, v45, v45
	v_max_f32_e32 v69, v44, v44
	v_max_f32_e32 v68, v69, v68
	v_max3_f32 v67, v30, v31, v67
	v_max3_f32 v68, v42, v43, v68
	v_max3_f32 v66, v66, v67, v68
	v_max_f32_e32 v67, v41, v41
	v_max_f32_e32 v68, v40, v40
	v_max_f32_e32 v67, v68, v67
	v_max_f32_e32 v68, v53, v53
	v_max_f32_e32 v69, v52, v52
	v_max_f32_e32 v68, v69, v68
	v_max3_f32 v67, v38, v39, v67
	v_max3_f32 v68, v50, v51, v68
	v_max3_f32 v66, v66, v67, v68
	v_max_f32_e32 v67, v49, v49
	v_max_f32_e32 v68, v48, v48
	v_max_f32_e32 v67, v68, v67
	v_max_f32_e32 v68, v61, v61
	v_max_f32_e32 v69, v60, v60
	v_max_f32_e32 v68, v69, v68
	v_max3_f32 v67, v46, v47, v67
	v_max3_f32 v68, v58, v59, v68
	v_max3_f32 v66, v66, v67, v68
	v_max_f32_e32 v67, v57, v57
	v_max_f32_e32 v68, v56, v56
	v_max_f32_e32 v67, v68, v67
	v_max_f32_e32 v68, v65, v65
	v_max_f32_e32 v69, v64, v64
	v_max_f32_e32 v68, v69, v68
	v_max3_f32 v67, v54, v55, v67
	v_max3_f32 v68, v62, v63, v68
	v_max3_f32 v66, v66, v67, v68
	ds_bpermute_b32 v67, v181, v66
	v_lshlrev_b64 v[130:131], 11, v[162:163]
	s_waitcnt lgkmcnt(0)
	v_max_f32_e32 v67, v67, v67
	v_max_f32_e32 v66, v66, v67
	ds_bpermute_b32 v67, v182, v66
	s_waitcnt lgkmcnt(0)
; __device__ __forceinline__ unsigned cvt_pk_bf16(float lo, float hi) { unsigned r; asm volatile("v_cvt_pk_bf16_f32 %0, %1, %2" : "=v"(r) : "v"(lo), "v"(hi)); return r; }
; __device__ __forceinline__ float fast_exp2(float x) { return __builtin_amdgcn_exp2f(x); }
; template <bool LOCAL>
; __device__ __forceinline__ void attn_unit(const bf16_t* Q, const bf16_t* KT, const bf16_t* VT, bf16_t* O, LAS unsigned char* lds, int b, int h, int r, int w, int tq, int lane) {
;     ...
;     float sum = 0.f; const float mxl = mx * 1.4426950408889634f;
;     bf16x8 pb[NP];
; #pragma unroll
;     for (int p = 0; p < NP; ++p) { float e[8];
; #pragma unroll
;         for (int f = 0; f < 2; ++f)
; #pragma unroll
;             for (int j = 0; j < 4; ++j) { e[4 * f + j] = fast_exp2(fmaf(s[2 * p + f][j], 1.4426950408889634f, -mxl)); sum += e[4 * f + j]; }
;         u32x4 pw; pw.x = cvt_pk_bf16(e[0], e[1]); pw.y = cvt_pk_bf16(e[2], e[3]); pw.z = cvt_pk_bf16(e[4], e[5]); pw.w = cvt_pk_bf16(e[6], e[7]);
;         pb[p] = __builtin_bit_cast(bf16x8, pw); }
	v_max_f32_e32 v67, v67, v67
	v_max_f32_e32 v66, v66, v67
	v_mul_f32_e32 v106, 0xbfb8aa3b, v66
	v_fmamk_f32 v66, v133, 0x3fb8aa3b, v106
	v_exp_f32_e32 v66, v66
	v_fmamk_f32 v68, v132, 0x3fb8aa3b, v106
	v_exp_f32_e32 v68, v68
	v_fmamk_f32 v69, v134, 0x3fb8aa3b, v106
	v_exp_f32_e32 v69, v69
	v_fmamk_f32 v70, v126, 0x3fb8aa3b, v106
	v_exp_f32_e32 v70, v70
	v_fmamk_f32 v71, v128, 0x3fb8aa3b, v106
	v_add_f32_e32 v67, 0, v66
	v_exp_f32_e32 v71, v71
	v_fmamk_f32 v72, v127, 0x3fb8aa3b, v106
	v_add_f32_e32 v67, v68, v67
	v_exp_f32_e32 v72, v72
	v_fmamk_f32 v73, v129, 0x3fb8aa3b, v106
	v_add_f32_e32 v67, v69, v67
	v_exp_f32_e32 v73, v73
	v_fmamk_f32 v74, v123, 0x3fb8aa3b, v106
	v_add_f32_e32 v67, v70, v67
	v_exp_f32_e32 v74, v74
	v_add_f32_e32 v67, v71, v67
	v_add_f32_e32 v67, v72, v67
	v_add_f32_e32 v67, v73, v67
	v_add_f32_e32 v75, v74, v67
	v_cvt_pk_bf16_f32 v66, v66, v68
	v_cvt_pk_bf16_f32 v67, v69, v70
	v_fmamk_f32 v70, v124, 0x3fb8aa3b, v106
	v_exp_f32_e32 v70, v70
	v_cvt_pk_bf16_f32 v68, v71, v72
	v_fmamk_f32 v72, v122, 0x3fb8aa3b, v106
	v_cvt_pk_bf16_f32 v69, v73, v74
	v_exp_f32_e32 v72, v72
	v_fmamk_f32 v73, v125, 0x3fb8aa3b, v106
	v_exp_f32_e32 v73, v73
	v_fmamk_f32 v74, v118, 0x3fb8aa3b, v106
	v_add_f32_e32 v71, v70, v75
	v_exp_f32_e32 v74, v74
	v_fmamk_f32 v75, v120, 0x3fb8aa3b, v106
	v_exp_f32_e32 v75, v75
	v_fmamk_f32 v76, v119, 0x3fb8aa3b, v106
	v_add_f32_e32 v71, v72, v71
	v_exp_f32_e32 v76, v76
	v_fmamk_f32 v77, v121, 0x3fb8aa3b, v106
	v_add_f32_e32 v71, v73, v71
	v_exp_f32_e32 v77, v77
	v_fmamk_f32 v78, v115, 0x3fb8aa3b, v106
	v_add_f32_e32 v71, v74, v71
	v_exp_f32_e32 v78, v78
	v_add_f32_e32 v71, v75, v71
	v_add_f32_e32 v71, v76, v71
	v_add_f32_e32 v71, v77, v71
	v_add_f32_e32 v79, v78, v71
	v_cvt_pk_bf16_f32 v70, v70, v72
	v_cvt_pk_bf16_f32 v71, v73, v74
	v_fmamk_f32 v74, v116, 0x3fb8aa3b, v106
	v_exp_f32_e32 v74, v74
	v_cvt_pk_bf16_f32 v72, v75, v76
	v_fmamk_f32 v76, v114, 0x3fb8aa3b, v106
	v_cvt_pk_bf16_f32 v73, v77, v78
	v_exp_f32_e32 v76, v76
	v_fmamk_f32 v77, v117, 0x3fb8aa3b, v106
	v_exp_f32_e32 v77, v77
	v_fmamk_f32 v78, v110, 0x3fb8aa3b, v106
	v_add_f32_e32 v75, v74, v79
	v_exp_f32_e32 v78, v78
	v_fmamk_f32 v79, v112, 0x3fb8aa3b, v106
	v_exp_f32_e32 v79, v79
	v_fmamk_f32 v80, v111, 0x3fb8aa3b, v106
	v_add_f32_e32 v75, v76, v75
	v_exp_f32_e32 v80, v80
	v_fmamk_f32 v81, v135, 0x3fb8aa3b, v106
	v_add_f32_e32 v75, v77, v75
	v_exp_f32_e32 v81, v81
	v_fmamk_f32 v82, v113, 0x3fb8aa3b, v106
	v_add_f32_e32 v75, v78, v75
	v_exp_f32_e32 v82, v82
	v_add_f32_e32 v75, v79, v75
	v_add_f32_e32 v75, v80, v75
	v_add_f32_e32 v75, v81, v75
	v_add_f32_e32 v83, v82, v75
	v_cvt_pk_bf16_f32 v74, v74, v76
	v_cvt_pk_bf16_f32 v75, v77, v78
	v_fmamk_f32 v78, v108, 0x3fb8aa3b, v106
	v_exp_f32_e32 v78, v78
	v_cvt_pk_bf16_f32 v76, v79, v80
	v_fmamk_f32 v80, v107, 0x3fb8aa3b, v106
	v_cvt_pk_bf16_f32 v77, v81, v82
	v_exp_f32_e32 v80, v80
	v_fmamk_f32 v81, v109, 0x3fb8aa3b, v106
	v_exp_f32_e32 v81, v81
	v_fmamk_f32 v82, v102, 0x3fb8aa3b, v106
	v_add_f32_e32 v79, v78, v83
	v_exp_f32_e32 v82, v82
	v_fmamk_f32 v83, v104, 0x3fb8aa3b, v106
	v_exp_f32_e32 v83, v83
	v_fmamk_f32 v84, v103, 0x3fb8aa3b, v106
	v_add_f32_e32 v79, v80, v79
	v_exp_f32_e32 v84, v84
	v_fmamk_f32 v85, v105, 0x3fb8aa3b, v106
	v_add_f32_e32 v79, v81, v79
	v_exp_f32_e32 v85, v85
	v_fmamk_f32 v99, v99, 0x3fb8aa3b, v106
	v_add_f32_e32 v79, v82, v79
	v_exp_f32_e32 v99, v99
	v_add_f32_e32 v79, v83, v79
	v_add_f32_e32 v79, v84, v79
	v_add_f32_e32 v79, v85, v79
	v_add_f32_e32 v102, v99, v79
	v_cvt_pk_bf16_f32 v78, v78, v80
	v_cvt_pk_bf16_f32 v79, v81, v82
	v_fmamk_f32 v82, v100, 0x3fb8aa3b, v106
	v_cvt_pk_bf16_f32 v80, v83, v84
	v_exp_f32_e32 v82, v82
	v_fmamk_f32 v84, v98, 0x3fb8aa3b, v106
	v_cvt_pk_bf16_f32 v81, v85, v99
	v_exp_f32_e32 v84, v84
	v_fmamk_f32 v85, v101, 0x3fb8aa3b, v106
	v_exp_f32_e32 v85, v85
	v_fmamk_f32 v94, v94, 0x3fb8aa3b, v106
	v_exp_f32_e32 v94, v94
	v_fmamk_f32 v96, v96, 0x3fb8aa3b, v106
	v_add_f32_e32 v83, v82, v102
	v_exp_f32_e32 v96, v96
	v_fmamk_f32 v95, v95, 0x3fb8aa3b, v106
	v_add_f32_e32 v83, v84, v83
	v_exp_f32_e32 v95, v95
	v_fmamk_f32 v97, v97, 0x3fb8aa3b, v106
	v_add_f32_e32 v83, v85, v83
	v_exp_f32_e32 v97, v97
	v_fmamk_f32 v91, v91, 0x3fb8aa3b, v106
	v_add_f32_e32 v83, v94, v83
	v_exp_f32_e32 v91, v91
	v_add_f32_e32 v83, v96, v83
	v_add_f32_e32 v83, v95, v83
	v_add_f32_e32 v83, v97, v83
	v_add_f32_e32 v98, v91, v83
	v_cvt_pk_bf16_f32 v82, v82, v84
	v_cvt_pk_bf16_f32 v83, v85, v94
	v_cvt_pk_bf16_f32 v84, v96, v95
	v_cvt_pk_bf16_f32 v85, v97, v91
	v_fmamk_f32 v91, v92, 0x3fb8aa3b, v106
	v_exp_f32_e32 v91, v91
	v_fmamk_f32 v90, v90, 0x3fb8aa3b, v106
	v_exp_f32_e32 v90, v90
	v_fmamk_f32 v93, v93, 0x3fb8aa3b, v106
	v_exp_f32_e32 v93, v93
	v_fmamk_f32 v86, v86, 0x3fb8aa3b, v106
	v_exp_f32_e32 v94, v86
	v_add_f32_e32 v92, v91, v98
	v_add_f32_e32 v92, v90, v92
	v_fmamk_f32 v88, v88, 0x3fb8aa3b, v106
	v_add_f32_e32 v92, v93, v92
	v_exp_f32_e32 v88, v88
	v_fmamk_f32 v87, v87, 0x3fb8aa3b, v106
	v_add_f32_e32 v86, v94, v92
	v_exp_f32_e32 v92, v87
	v_fmamk_f32 v87, v138, 0x3fb8aa3b, v106
	v_exp_f32_e32 v95, v87
	v_fmamk_f32 v87, v89, 0x3fb8aa3b, v106
	v_exp_f32_e32 v89, v87
	v_add_f32_e32 v86, v88, v86
	v_add_f32_e32 v86, v92, v86
	v_add_f32_e32 v86, v95, v86
	v_add_f32_e32 v96, v89, v86
	v_cvt_pk_bf16_f32 v86, v91, v90
	v_fmamk_f32 v90, v137, 0x3fb8aa3b, v106
	v_cvt_pk_bf16_f32 v87, v93, v94
	v_cvt_pk_bf16_f32 v88, v88, v92
	v_exp_f32_e32 v90, v90
	v_fmamk_f32 v92, v136, 0x3fb8aa3b, v106
	v_exp_f32_e32 v92, v92
	v_fmamk_f32 v93, v141, 0x3fb8aa3b, v106
	v_exp_f32_e32 v93, v93
	v_fmamk_f32 v94, v139, 0x3fb8aa3b, v106
	v_cvt_pk_bf16_f32 v89, v95, v89
	v_exp_f32_e32 v95, v94
; __device__ __forceinline__ unsigned cvt_pk_bf16(float lo, float hi) { unsigned r; asm volatile("v_cvt_pk_bf16_f32 %0, %1, %2" : "=v"(r) : "v"(lo), "v"(hi)); return r; }
; __device__ __forceinline__ float fast_exp2(float x) { return __builtin_amdgcn_exp2f(x); }
; template <bool LOCAL>
; __device__ __forceinline__ void attn_unit(const bf16_t* Q, const bf16_t* KT, const bf16_t* VT, bf16_t* O, LAS unsigned char* lds, int b, int h, int r, int w, int tq, int lane) {
;     ...
;     float sum = 0.f; const float mxl = mx * 1.4426950408889634f;
;     bf16x8 pb[NP];
; #pragma unroll
;     for (int p = 0; p < NP; ++p) { float e[8];
; #pragma unroll
;         for (int f = 0; f < 2; ++f)
; #pragma unroll
;             for (int j = 0; j < 4; ++j) { e[4 * f + j] = fast_exp2(fmaf(s[2 * p + f][j], 1.4426950408889634f, -mxl)); sum += e[4 * f + j]; }
;         u32x4 pw; pw.x = cvt_pk_bf16(e[0], e[1]); pw.y = cvt_pk_bf16(e[2], e[3]); pw.z = cvt_pk_bf16(e[4], e[5]); pw.w = cvt_pk_bf16(e[6], e[7]);
;         pb[p] = __builtin_bit_cast(bf16x8, pw); }
	v_fmamk_f32 v94, v195, 0x3fb8aa3b, v106
	v_add_f32_e32 v91, v90, v96
	v_exp_f32_e32 v96, v94
	v_fmamk_f32 v94, v140, 0x3fb8aa3b, v106
	v_add_f32_e32 v91, v92, v91
	v_exp_f32_e32 v97, v94
	v_fmamk_f32 v94, v199, 0x3fb8aa3b, v106
	v_add_f32_e32 v91, v93, v91
	v_exp_f32_e32 v98, v94
	v_fmamk_f32 v94, v197, 0x3fb8aa3b, v106
	v_add_f32_e32 v91, v95, v91
	v_exp_f32_e32 v99, v94
	v_cvt_pk_bf16_f32 v94, v90, v92
	v_fmamk_f32 v90, v198, 0x3fb8aa3b, v106
	v_add_f32_e32 v91, v96, v91
	v_exp_f32_e32 v90, v90
	v_fmamk_f32 v92, v196, 0x3fb8aa3b, v106
	v_add_f32_e32 v91, v97, v91
	v_cvt_pk_bf16_f32 v95, v93, v95
	v_exp_f32_e32 v92, v92
	v_fmamk_f32 v93, v202, 0x3fb8aa3b, v106
	v_add_f32_e32 v91, v98, v91
	v_cvt_pk_bf16_f32 v96, v96, v97
	v_cvt_pk_bf16_f32 v97, v98, v99
	v_exp_f32_e32 v93, v93
	v_fmamk_f32 v98, v200, 0x3fb8aa3b, v106
	v_add_f32_e32 v91, v99, v91
	v_exp_f32_e32 v98, v98
	v_fmamk_f32 v99, v203, 0x3fb8aa3b, v106
	v_add_f32_e32 v91, v90, v91
	v_exp_f32_e32 v99, v99
	v_fmamk_f32 v100, v201, 0x3fb8aa3b, v106
	v_add_f32_e32 v91, v92, v91
	v_exp_f32_e32 v100, v100
	v_fmamk_f32 v101, v205, 0x3fb8aa3b, v106
	v_add_f32_e32 v91, v93, v91
	v_exp_f32_e32 v101, v101
	v_fmamk_f32 v102, v204, 0x3fb8aa3b, v106
	v_add_f32_e32 v91, v98, v91
	v_exp_f32_e32 v105, v102
	v_fmamk_f32 v2, v2, 0x3fb8aa3b, v106
	v_add_f32_e32 v91, v99, v91
	v_exp_f32_e32 v2, v2
	v_fmamk_f32 v3, v3, 0x3fb8aa3b, v106
	v_add_f32_e32 v91, v100, v91
	v_exp_f32_e32 v3, v3
	v_fmamk_f32 v4, v4, 0x3fb8aa3b, v106
	v_add_f32_e32 v91, v101, v91
	v_exp_f32_e32 v4, v4
	v_fmamk_f32 v5, v5, 0x3fb8aa3b, v106
	v_add_f32_e32 v91, v105, v91
	v_exp_f32_e32 v5, v5
	v_fmamk_f32 v10, v10, 0x3fb8aa3b, v106
	v_cvt_pk_bf16_f32 v102, v90, v92
	v_add_f32_e32 v90, v2, v91
	v_exp_f32_e32 v10, v10
	v_fmamk_f32 v11, v11, 0x3fb8aa3b, v106
	v_add_f32_e32 v90, v3, v90
	v_exp_f32_e32 v11, v11
	v_fmamk_f32 v12, v12, 0x3fb8aa3b, v106
	v_add_f32_e32 v90, v4, v90
	v_exp_f32_e32 v12, v12
	v_fmamk_f32 v13, v13, 0x3fb8aa3b, v106
	v_cvt_pk_bf16_f32 v103, v93, v98
	v_cvt_pk_bf16_f32 v104, v99, v100
	v_cvt_pk_bf16_f32 v105, v101, v105
	v_add_f32_e32 v90, v5, v90
	v_exp_f32_e32 v13, v13
	v_cvt_pk_bf16_f32 v98, v2, v3
	v_fmamk_f32 v2, v6, 0x3fb8aa3b, v106
	v_add_f32_e32 v90, v10, v90
	v_cvt_pk_bf16_f32 v99, v4, v5
	v_exp_f32_e32 v2, v2
	v_fmamk_f32 v4, v7, 0x3fb8aa3b, v106
	v_add_f32_e32 v90, v11, v90
	v_exp_f32_e32 v4, v4
	v_fmamk_f32 v5, v8, 0x3fb8aa3b, v106
	v_add_f32_e32 v90, v12, v90
	v_exp_f32_e32 v5, v5
	v_fmamk_f32 v6, v9, 0x3fb8aa3b, v106
	v_add_f32_e32 v90, v13, v90
	v_exp_f32_e32 v6, v6
	v_fmamk_f32 v7, v18, 0x3fb8aa3b, v106
	v_add_f32_e32 v3, v2, v90
	v_exp_f32_e32 v7, v7
	v_fmamk_f32 v8, v19, 0x3fb8aa3b, v106
	v_add_f32_e32 v3, v4, v3
	v_exp_f32_e32 v8, v8
	v_fmamk_f32 v9, v20, 0x3fb8aa3b, v106
	v_cvt_pk_bf16_f32 v100, v10, v11
	v_add_f32_e32 v3, v5, v3
	v_exp_f32_e32 v9, v9
	v_fmamk_f32 v10, v21, 0x3fb8aa3b, v106
	v_cvt_pk_bf16_f32 v101, v12, v13
	v_add_f32_e32 v3, v6, v3
	v_exp_f32_e32 v10, v10
	v_cvt_pk_bf16_f32 v90, v2, v4
	v_fmamk_f32 v2, v14, 0x3fb8aa3b, v106
	v_add_f32_e32 v3, v7, v3
	v_exp_f32_e32 v2, v2
	v_fmamk_f32 v4, v15, 0x3fb8aa3b, v106
	v_add_f32_e32 v3, v8, v3
	v_cvt_pk_bf16_f32 v91, v5, v6
	v_exp_f32_e32 v4, v4
	v_fmamk_f32 v5, v16, 0x3fb8aa3b, v106
	v_add_f32_e32 v3, v9, v3
	v_exp_f32_e32 v5, v5
	v_fmamk_f32 v6, v17, 0x3fb8aa3b, v106
	v_add_f32_e32 v3, v10, v3
	v_cvt_pk_bf16_f32 v92, v7, v8
	v_exp_f32_e32 v6, v6
	v_fmamk_f32 v7, v26, 0x3fb8aa3b, v106
	v_add_f32_e32 v3, v2, v3
	v_exp_f32_e32 v7, v7
	v_fmamk_f32 v8, v27, 0x3fb8aa3b, v106
	v_cvt_pk_bf16_f32 v93, v9, v10
	v_add_f32_e32 v3, v4, v3
	v_exp_f32_e32 v8, v8
	v_fmamk_f32 v9, v28, 0x3fb8aa3b, v106
	v_add_f32_e32 v3, v5, v3
	v_exp_f32_e32 v9, v9
	v_fmamk_f32 v10, v29, 0x3fb8aa3b, v106
	v_add_f32_e32 v3, v6, v3
	v_exp_f32_e32 v10, v10
	v_cvt_pk_bf16_f32 v26, v2, v4
	v_fmamk_f32 v2, v22, 0x3fb8aa3b, v106
	v_add_f32_e32 v3, v7, v3
	v_exp_f32_e32 v2, v2
	v_fmamk_f32 v4, v23, 0x3fb8aa3b, v106
	v_add_f32_e32 v3, v8, v3
	v_cvt_pk_bf16_f32 v27, v5, v6
	v_exp_f32_e32 v4, v4
	v_fmamk_f32 v5, v24, 0x3fb8aa3b, v106
	v_add_f32_e32 v3, v9, v3
	v_exp_f32_e32 v5, v5
	v_fmamk_f32 v6, v25, 0x3fb8aa3b, v106
	v_add_f32_e32 v3, v10, v3
	v_cvt_pk_bf16_f32 v28, v7, v8
	v_exp_f32_e32 v6, v6
	v_fmamk_f32 v7, v34, 0x3fb8aa3b, v106
	v_add_f32_e32 v3, v2, v3
	v_exp_f32_e32 v7, v7
	v_fmamk_f32 v8, v35, 0x3fb8aa3b, v106
	v_cvt_pk_bf16_f32 v29, v9, v10
	v_add_f32_e32 v3, v4, v3
	v_exp_f32_e32 v8, v8
	v_fmamk_f32 v9, v36, 0x3fb8aa3b, v106
	v_add_f32_e32 v3, v5, v3
	v_exp_f32_e32 v9, v9
	v_fmamk_f32 v10, v37, 0x3fb8aa3b, v106
	v_add_f32_e32 v3, v6, v3
	v_exp_f32_e32 v13, v10
	v_cvt_pk_bf16_f32 v10, v2, v4
	v_fmamk_f32 v2, v30, 0x3fb8aa3b, v106
	v_add_f32_e32 v3, v7, v3
	v_exp_f32_e32 v2, v2
	v_fmamk_f32 v4, v31, 0x3fb8aa3b, v106
	v_add_f32_e32 v3, v8, v3
	v_cvt_pk_bf16_f32 v11, v5, v6
	v_exp_f32_e32 v4, v4
	v_fmamk_f32 v5, v32, 0x3fb8aa3b, v106
	v_add_f32_e32 v3, v9, v3
	v_exp_f32_e32 v5, v5
	v_fmamk_f32 v6, v33, 0x3fb8aa3b, v106
	v_add_f32_e32 v3, v13, v3
	v_cvt_pk_bf16_f32 v12, v7, v8
	v_exp_f32_e32 v6, v6
	v_fmamk_f32 v7, v42, 0x3fb8aa3b, v106
	v_add_f32_e32 v3, v2, v3
	v_exp_f32_e32 v7, v7
	v_fmamk_f32 v8, v43, 0x3fb8aa3b, v106
	v_cvt_pk_bf16_f32 v13, v9, v13
	v_add_f32_e32 v3, v4, v3
	v_exp_f32_e32 v8, v8
	v_fmamk_f32 v9, v44, 0x3fb8aa3b, v106
	v_add_f32_e32 v3, v5, v3
	v_exp_f32_e32 v9, v9
	v_fmamk_f32 v14, v45, 0x3fb8aa3b, v106
	v_add_f32_e32 v3, v6, v3
	v_exp_f32_e32 v14, v14
	v_add_f32_e32 v3, v7, v3
	v_add_f32_e32 v3, v8, v3
	v_add_f32_e32 v3, v9, v3
	v_add_f32_e32 v15, v14, v3
	v_cvt_pk_bf16_f32 v2, v2, v4
	v_cvt_pk_bf16_f32 v3, v5, v6
	v_fmamk_f32 v6, v38, 0x3fb8aa3b, v106
; __device__ __forceinline__ unsigned cvt_pk_bf16(float lo, float hi) { unsigned r; asm volatile("v_cvt_pk_bf16_f32 %0, %1, %2" : "=v"(r) : "v"(lo), "v"(hi)); return r; }
; __device__ __forceinline__ float fast_exp2(float x) { return __builtin_amdgcn_exp2f(x); }
; #define ATT_VLOAD(buf, p) do { const bf16_t* vp_ = vloc + (size_t)((p) * 8 * NH) * 1024; \
;         _Pragma("unroll") for (int df = 0; df < 8; ++df) va[buf][df] = *(const bf16x8*)(vp_ + df * 128); } while (0)
; template <bool LOCAL>
; __device__ __forceinline__ void attn_unit(const bf16_t* Q, const bf16_t* KT, const bf16_t* VT, bf16_t* O, LAS unsigned char* lds, int b, int h, int r, int w, int tq, int lane) {
;     ...
;     float sum = 0.f; const float mxl = mx * 1.4426950408889634f;
;     bf16x8 pb[NP];
; #pragma unroll
;     for (int p = 0; p < NP; ++p) { float e[8];
; #pragma unroll
;         for (int f = 0; f < 2; ++f)
; #pragma unroll
;             for (int j = 0; j < 4; ++j) { e[4 * f + j] = fast_exp2(fmaf(s[2 * p + f][j], 1.4426950408889634f, -mxl)); sum += e[4 * f + j]; }
;         u32x4 pw; pw.x = cvt_pk_bf16(e[0], e[1]); pw.y = cvt_pk_bf16(e[2], e[3]); pw.z = cvt_pk_bf16(e[4], e[5]); pw.w = cvt_pk_bf16(e[6], e[7]);
;         pb[p] = __builtin_bit_cast(bf16x8, pw); }
;     sum += __shfl_xor(sum, 16); sum += __shfl_xor(sum, 32);
;     f32x4 o[8];
; #pragma unroll
;     for (int df = 0; df < 8; ++df) o[df] = (f32x4){0.f, 0.f, 0.f, 0.f};
;     if (LOCAL) {
;         const bf16_t* vloc = VT + ((size_t)(((rgl >> 3) + g) * NH + h)) * 1024 + q * 8;
;         bf16x8 va[2][8];
;     ...
;         ATT_VLOAD(0, 0);
; #pragma unroll
;         for (int p = 0; p < 8; ++p) {
;             __builtin_amdgcn_s_barrier();
;             if (p + 1 < 8) ATT_VLOAD((p + 1) & 1, p + 1);
;             __builtin_amdgcn_sched_barrier(0);
; #pragma unroll
;             for (int df = 0; df < 8; ++df) o[df] = __builtin_amdgcn_mfma_f32_16x16x32_bf16(va[p & 1][df], pb[p], o[df], 0, 0, 0);
;             __builtin_amdgcn_sched_barrier(0);
;         }
;     ...
;     }
	v_exp_f32_e32 v6, v6
	v_cvt_pk_bf16_f32 v4, v7, v8
	v_fmamk_f32 v8, v39, 0x3fb8aa3b, v106
	v_cvt_pk_bf16_f32 v5, v9, v14
	v_exp_f32_e32 v8, v8
	v_fmamk_f32 v9, v40, 0x3fb8aa3b, v106
	v_exp_f32_e32 v9, v9
	v_fmamk_f32 v14, v41, 0x3fb8aa3b, v106
	v_add_f32_e32 v7, v6, v15
	v_exp_f32_e32 v14, v14
	v_fmamk_f32 v15, v50, 0x3fb8aa3b, v106
	v_exp_f32_e32 v15, v15
	v_fmamk_f32 v16, v51, 0x3fb8aa3b, v106
	v_add_f32_e32 v7, v8, v7
	v_exp_f32_e32 v16, v16
	v_fmamk_f32 v17, v52, 0x3fb8aa3b, v106
	v_add_f32_e32 v7, v9, v7
	v_exp_f32_e32 v17, v17
	v_fmamk_f32 v18, v53, 0x3fb8aa3b, v106
	v_add_f32_e32 v7, v14, v7
	v_exp_f32_e32 v18, v18
	v_add_f32_e32 v7, v15, v7
	v_add_f32_e32 v7, v16, v7
	v_add_f32_e32 v7, v17, v7
	v_add_f32_e32 v19, v18, v7
	v_cvt_pk_bf16_f32 v6, v6, v8
	v_cvt_pk_bf16_f32 v7, v9, v14
	v_fmamk_f32 v14, v46, 0x3fb8aa3b, v106
	v_exp_f32_e32 v14, v14
	v_cvt_pk_bf16_f32 v8, v15, v16
	v_fmamk_f32 v16, v47, 0x3fb8aa3b, v106
	v_cvt_pk_bf16_f32 v9, v17, v18
	v_exp_f32_e32 v16, v16
	v_fmamk_f32 v17, v48, 0x3fb8aa3b, v106
	v_exp_f32_e32 v17, v17
	v_fmamk_f32 v18, v49, 0x3fb8aa3b, v106
	v_add_f32_e32 v15, v14, v19
	v_exp_f32_e32 v18, v18
	v_fmamk_f32 v19, v58, 0x3fb8aa3b, v106
	v_exp_f32_e32 v19, v19
	v_fmamk_f32 v20, v59, 0x3fb8aa3b, v106
	v_add_f32_e32 v15, v16, v15
	v_exp_f32_e32 v20, v20
	v_fmamk_f32 v21, v60, 0x3fb8aa3b, v106
	v_add_f32_e32 v15, v17, v15
	v_exp_f32_e32 v21, v21
	v_fmamk_f32 v22, v61, 0x3fb8aa3b, v106
	v_add_f32_e32 v15, v18, v15
	v_exp_f32_e32 v22, v22
	v_add_f32_e32 v15, v19, v15
	v_add_f32_e32 v15, v20, v15
	v_add_f32_e32 v15, v21, v15
	v_add_f32_e32 v23, v22, v15
	v_cvt_pk_bf16_f32 v14, v14, v16
	v_cvt_pk_bf16_f32 v15, v17, v18
	v_fmamk_f32 v18, v54, 0x3fb8aa3b, v106
	v_exp_f32_e32 v18, v18
	v_cvt_pk_bf16_f32 v16, v19, v20
	v_fmamk_f32 v20, v55, 0x3fb8aa3b, v106
	v_cvt_pk_bf16_f32 v17, v21, v22
	v_exp_f32_e32 v20, v20
	v_fmamk_f32 v21, v56, 0x3fb8aa3b, v106
	v_exp_f32_e32 v21, v21
	v_fmamk_f32 v22, v57, 0x3fb8aa3b, v106
	v_add_f32_e32 v19, v18, v23
	v_exp_f32_e32 v22, v22
	v_fmamk_f32 v23, v62, 0x3fb8aa3b, v106
	v_exp_f32_e32 v23, v23
	v_fmamk_f32 v24, v63, 0x3fb8aa3b, v106
	v_add_f32_e32 v19, v20, v19
	v_exp_f32_e32 v24, v24
	v_fmamk_f32 v25, v64, 0x3fb8aa3b, v106
	v_add_f32_e32 v19, v21, v19
	v_exp_f32_e32 v25, v25
	v_fmac_f32_e32 v106, 0x3fb8aa3b, v65
	v_add_f32_e32 v19, v22, v19
	v_exp_f32_e32 v30, v106
	v_add_f32_e32 v19, v23, v19
	v_add_f32_e32 v19, v24, v19
	v_add_f32_e32 v19, v25, v19
	v_add_f32_e32 v31, v30, v19
	v_cvt_pk_bf16_f32 v18, v18, v20
	v_cvt_pk_bf16_f32 v19, v21, v22
	ds_bpermute_b32 v22, v181, v31
	v_cvt_pk_bf16_f32 v20, v23, v24
	v_cvt_pk_bf16_f32 v21, v25, v30
	s_waitcnt lgkmcnt(0)
	v_add_f32_e32 v134, v31, v22
	v_add_u32_e32 v22, v194, v165
	v_lshl_or_b32 v22, v22, 4, s72
	v_ashrrev_i32_e32 v23, 31, v22
	v_lshlrev_b64 v[22:23], 11, v[22:23]
	v_lshl_add_u64 v[132:133], v[148:149], 0, v[22:23]
	ds_bpermute_b32 v135, v182, v134
	s_cmp_eq_u32 s53, 0
	s_cbranch_scc0 .Lrg_v_B
	s_waitcnt vmcnt(6)
	s_barrier
	ds_read_b128 v[106:109], v219 offset:0
	ds_read_b128 v[110:113], v219 offset:256
	ds_read_b128 v[114:117], v219 offset:512
	ds_read_b128 v[118:121], v219 offset:768
	s_waitcnt vmcnt(5)
	s_barrier
	ds_read_b128 v[122:125], v219 offset:8192
	ds_read_b128 v[126:129], v219 offset:8448
	ds_read_b128 v[58:61], v219 offset:8704
	ds_read_b128 v[62:65], v219 offset:8960
	s_waitcnt lgkmcnt(4)
	v_mfma_f32_16x16x32_bf16 v[22:25], v[106:109], v[66:69], 0
	v_mfma_f32_16x16x32_bf16 v[30:33], v[110:113], v[66:69], 0
	v_mfma_f32_16x16x32_bf16 v[34:37], v[114:117], v[66:69], 0
	v_mfma_f32_16x16x32_bf16 v[38:41], v[118:121], v[66:69], 0
	s_add_i32 m0, s59, 57344
	v_add_co_u32_e32 v222, vcc, s2, v226
	s_nop 1
	v_addc_co_u32_e32 v223, vcc, 0, v227, vcc
	global_load_lds_dwordx4 v[222:223], off
	s_waitcnt vmcnt(5)
	s_barrier
	ds_read_b128 v[106:109], v219 offset:16384
	ds_read_b128 v[110:113], v219 offset:16640
	ds_read_b128 v[114:117], v219 offset:16896
	ds_read_b128 v[118:121], v219 offset:17152
	s_waitcnt lgkmcnt(4)
	v_mfma_f32_16x16x32_bf16 v[42:45], v[122:125], v[66:69], 0
	v_mfma_f32_16x16x32_bf16 v[46:49], v[126:129], v[66:69], 0
	v_mfma_f32_16x16x32_bf16 v[50:53], v[58:61], v[66:69], 0
	v_mfma_f32_16x16x32_bf16 v[54:57], v[62:65], v[66:69], 0
	s_add_i32 m0, s59, 0
	v_add_co_u32_e32 v222, vcc, s60, v220
	s_nop 1
	v_addc_co_u32_e32 v223, vcc, 0, v221, vcc
	global_load_lds_dwordx4 v[222:223], off
	s_waitcnt vmcnt(5)
	s_barrier
	ds_read_b128 v[122:125], v219 offset:24576
	ds_read_b128 v[126:129], v219 offset:24832
	ds_read_b128 v[58:61], v219 offset:25088
	ds_read_b128 v[62:65], v219 offset:25344
	s_waitcnt lgkmcnt(4)
	v_mfma_f32_16x16x32_bf16 v[22:25], v[106:109], v[70:73], v[22:25]
	v_mfma_f32_16x16x32_bf16 v[30:33], v[110:113], v[70:73], v[30:33]
	v_mfma_f32_16x16x32_bf16 v[34:37], v[114:117], v[70:73], v[34:37]
	v_mfma_f32_16x16x32_bf16 v[38:41], v[118:121], v[70:73], v[38:41]
	s_add_i32 m0, s59, 8192
	v_add_co_u32_e32 v222, vcc, s60, v226
	s_nop 1
	v_addc_co_u32_e32 v223, vcc, 0, v227, vcc
	global_load_lds_dwordx4 v[222:223], off
	s_waitcnt vmcnt(5)
	s_barrier
	ds_read_b128 v[106:109], v219 offset:32768
	ds_read_b128 v[110:113], v219 offset:33024
	ds_read_b128 v[114:117], v219 offset:33280
	ds_read_b128 v[118:121], v219 offset:33536
	s_waitcnt lgkmcnt(4)
	v_mfma_f32_16x16x32_bf16 v[42:45], v[122:125], v[70:73], v[42:45]
	v_mfma_f32_16x16x32_bf16 v[46:49], v[126:129], v[70:73], v[46:49]
	v_mfma_f32_16x16x32_bf16 v[50:53], v[58:61], v[70:73], v[50:53]
	v_mfma_f32_16x16x32_bf16 v[54:57], v[62:65], v[70:73], v[54:57]
	s_add_i32 m0, s59, 16384
	v_add_co_u32_e32 v222, vcc, s61, v220
	s_nop 1
	v_addc_co_u32_e32 v223, vcc, 0, v221, vcc
	global_load_lds_dwordx4 v[222:223], off
	s_waitcnt vmcnt(5)
	s_barrier
; #define ATT_VLOAD(buf, p) do { const bf16_t* vp_ = vloc + (size_t)((p) * 8 * NH) * 1024; \
;         _Pragma("unroll") for (int df = 0; df < 8; ++df) va[buf][df] = *(const bf16x8*)(vp_ + df * 128); } while (0)
; template <bool LOCAL>
; __device__ __forceinline__ void attn_unit(const bf16_t* Q, const bf16_t* KT, const bf16_t* VT, bf16_t* O, LAS unsigned char* lds, int b, int h, int r, int w, int tq, int lane) {
;     ...
;     if (LOCAL) {
;         const bf16_t* vloc = VT + ((size_t)(((rgl >> 3) + g) * NH + h)) * 1024 + q * 8;
;         bf16x8 va[2][8];
;     ...
;         ATT_VLOAD(0, 0);
; #pragma unroll
;         for (int p = 0; p < 8; ++p) {
;             __builtin_amdgcn_s_barrier();
;             if (p + 1 < 8) ATT_VLOAD((p + 1) & 1, p + 1);
;             __builtin_amdgcn_sched_barrier(0);
; #pragma unroll
;             for (int df = 0; df < 8; ++df) o[df] = __builtin_amdgcn_mfma_f32_16x16x32_bf16(va[p & 1][df], pb[p], o[df], 0, 0, 0);
;             __builtin_amdgcn_sched_barrier(0);
;         }
;     ...
;     }
	ds_read_b128 v[122:125], v219 offset:40960
	ds_read_b128 v[126:129], v219 offset:41216
	ds_read_b128 v[58:61], v219 offset:41472
	ds_read_b128 v[62:65], v219 offset:41728
	s_waitcnt lgkmcnt(4)
	v_mfma_f32_16x16x32_bf16 v[22:25], v[106:109], v[74:77], v[22:25]
	v_mfma_f32_16x16x32_bf16 v[30:33], v[110:113], v[74:77], v[30:33]
	v_mfma_f32_16x16x32_bf16 v[34:37], v[114:117], v[74:77], v[34:37]
	v_mfma_f32_16x16x32_bf16 v[38:41], v[118:121], v[74:77], v[38:41]
	s_add_i32 m0, s59, 24576
	v_add_co_u32_e32 v222, vcc, s61, v226
	s_nop 1
	v_addc_co_u32_e32 v223, vcc, 0, v227, vcc
	global_load_lds_dwordx4 v[222:223], off
	s_waitcnt vmcnt(5)
	s_barrier
	ds_read_b128 v[106:109], v219 offset:49152
	ds_read_b128 v[110:113], v219 offset:49408
	ds_read_b128 v[114:117], v219 offset:49664
	ds_read_b128 v[118:121], v219 offset:49920
	s_waitcnt lgkmcnt(4)
	v_mfma_f32_16x16x32_bf16 v[42:45], v[122:125], v[74:77], v[42:45]
	v_mfma_f32_16x16x32_bf16 v[46:49], v[126:129], v[74:77], v[46:49]
	v_mfma_f32_16x16x32_bf16 v[50:53], v[58:61], v[74:77], v[50:53]
	v_mfma_f32_16x16x32_bf16 v[54:57], v[62:65], v[74:77], v[54:57]
	s_add_i32 m0, s59, 32768
	v_add_co_u32_e32 v222, vcc, s17, v220
	s_nop 1
	v_addc_co_u32_e32 v223, vcc, 0, v221, vcc
	global_load_lds_dwordx4 v[222:223], off
	s_waitcnt vmcnt(5)
	s_barrier
	ds_read_b128 v[122:125], v219 offset:57344
	ds_read_b128 v[126:129], v219 offset:57600
	ds_read_b128 v[58:61], v219 offset:57856
	ds_read_b128 v[62:65], v219 offset:58112
	s_waitcnt lgkmcnt(4)
	v_mfma_f32_16x16x32_bf16 v[22:25], v[106:109], v[78:81], v[22:25]
	v_mfma_f32_16x16x32_bf16 v[30:33], v[110:113], v[78:81], v[30:33]
	v_mfma_f32_16x16x32_bf16 v[34:37], v[114:117], v[78:81], v[34:37]
	v_mfma_f32_16x16x32_bf16 v[38:41], v[118:121], v[78:81], v[38:41]
	s_add_i32 m0, s59, 40960
	v_add_co_u32_e32 v222, vcc, s17, v226
	s_nop 1
	v_addc_co_u32_e32 v223, vcc, 0, v227, vcc
	global_load_lds_dwordx4 v[222:223], off
	s_waitcnt vmcnt(5)
	s_barrier
	ds_read_b128 v[106:109], v219 offset:0
	ds_read_b128 v[110:113], v219 offset:256
	ds_read_b128 v[114:117], v219 offset:512
	ds_read_b128 v[118:121], v219 offset:768
	s_waitcnt lgkmcnt(4)
	v_mfma_f32_16x16x32_bf16 v[42:45], v[122:125], v[78:81], v[42:45]
	v_mfma_f32_16x16x32_bf16 v[46:49], v[126:129], v[78:81], v[46:49]
	v_mfma_f32_16x16x32_bf16 v[50:53], v[58:61], v[78:81], v[50:53]
	v_mfma_f32_16x16x32_bf16 v[54:57], v[62:65], v[78:81], v[54:57]
	s_add_i32 m0, s59, 49152
	v_add_co_u32_e32 v222, vcc, s62, v220
	s_nop 1
	v_addc_co_u32_e32 v223, vcc, 0, v221, vcc
	global_load_lds_dwordx4 v[222:223], off
	s_waitcnt vmcnt(5)
	s_barrier
	ds_read_b128 v[122:125], v219 offset:8192
	ds_read_b128 v[126:129], v219 offset:8448
	ds_read_b128 v[58:61], v219 offset:8704
	ds_read_b128 v[62:65], v219 offset:8960
	s_waitcnt lgkmcnt(4)
	v_mfma_f32_16x16x32_bf16 v[22:25], v[106:109], v[82:85], v[22:25]
	v_mfma_f32_16x16x32_bf16 v[30:33], v[110:113], v[82:85], v[30:33]
	v_mfma_f32_16x16x32_bf16 v[34:37], v[114:117], v[82:85], v[34:37]
	v_mfma_f32_16x16x32_bf16 v[38:41], v[118:121], v[82:85], v[38:41]
	s_add_i32 m0, s59, 57344
	v_add_co_u32_e32 v222, vcc, s62, v226
	s_nop 1
	v_addc_co_u32_e32 v223, vcc, 0, v227, vcc
	global_load_lds_dwordx4 v[222:223], off
	s_waitcnt vmcnt(5)
	s_barrier
	ds_read_b128 v[106:109], v219 offset:16384
	ds_read_b128 v[110:113], v219 offset:16640
	ds_read_b128 v[114:117], v219 offset:16896
	ds_read_b128 v[118:121], v219 offset:17152
	s_waitcnt lgkmcnt(4)
	v_mfma_f32_16x16x32_bf16 v[42:45], v[122:125], v[82:85], v[42:45]
	v_mfma_f32_16x16x32_bf16 v[46:49], v[126:129], v[82:85], v[46:49]
	v_mfma_f32_16x16x32_bf16 v[50:53], v[58:61], v[82:85], v[50:53]
	v_mfma_f32_16x16x32_bf16 v[54:57], v[62:65], v[82:85], v[54:57]
	s_cmp_eq_u32 s73, 0
	s_cbranch_scc1 .Lrg_v_A_nd9
	s_add_i32 m0, s59, 0
	v_add_co_u32_e32 v222, vcc, s75, v220
	s_nop 1
	v_addc_co_u32_e32 v223, vcc, 0, v221, vcc
	global_load_lds_dwordx4 v[222:223], off
.Lrg_v_A_nd9:
	s_waitcnt vmcnt(4)
	s_barrier
	ds_read_b128 v[122:125], v219 offset:24576
	ds_read_b128 v[126:129], v219 offset:24832
	ds_read_b128 v[58:61], v219 offset:25088
	ds_read_b128 v[62:65], v219 offset:25344
	s_waitcnt lgkmcnt(4)
	v_mfma_f32_16x16x32_bf16 v[22:25], v[106:109], v[86:89], v[22:25]
	v_mfma_f32_16x16x32_bf16 v[30:33], v[110:113], v[86:89], v[30:33]
	v_mfma_f32_16x16x32_bf16 v[34:37], v[114:117], v[86:89], v[34:37]
	v_mfma_f32_16x16x32_bf16 v[38:41], v[118:121], v[86:89], v[38:41]
	s_cmp_eq_u32 s73, 0
	s_cbranch_scc1 .Lrg_v_A_nd10
	s_add_i32 m0, s59, 8192
	v_add_co_u32_e32 v222, vcc, s75, v226
	s_nop 1
	v_addc_co_u32_e32 v223, vcc, 0, v227, vcc
	global_load_lds_dwordx4 v[222:223], off
.Lrg_v_A_nd10:
	s_waitcnt vmcnt(3)
	s_barrier
	ds_read_b128 v[106:109], v219 offset:32768
	ds_read_b128 v[110:113], v219 offset:33024
	ds_read_b128 v[114:117], v219 offset:33280
	ds_read_b128 v[118:121], v219 offset:33536
	s_waitcnt lgkmcnt(4)
	v_mfma_f32_16x16x32_bf16 v[42:45], v[122:125], v[86:89], v[42:45]
	v_mfma_f32_16x16x32_bf16 v[46:49], v[126:129], v[86:89], v[46:49]
	v_mfma_f32_16x16x32_bf16 v[50:53], v[58:61], v[86:89], v[50:53]
	v_mfma_f32_16x16x32_bf16 v[54:57], v[62:65], v[86:89], v[54:57]
	s_waitcnt vmcnt(2)
	s_barrier
	ds_read_b128 v[122:125], v219 offset:40960
	ds_read_b128 v[126:129], v219 offset:41216
	ds_read_b128 v[58:61], v219 offset:41472
	ds_read_b128 v[62:65], v219 offset:41728
	s_waitcnt lgkmcnt(4)
	v_mfma_f32_16x16x32_bf16 v[22:25], v[106:109], v[94:97], v[22:25]
	v_mfma_f32_16x16x32_bf16 v[30:33], v[110:113], v[94:97], v[30:33]
	v_mfma_f32_16x16x32_bf16 v[34:37], v[114:117], v[94:97], v[34:37]
	v_mfma_f32_16x16x32_bf16 v[38:41], v[118:121], v[94:97], v[38:41]
	s_waitcnt vmcnt(1)
	s_barrier
	ds_read_b128 v[106:109], v219 offset:49152
	ds_read_b128 v[110:113], v219 offset:49408
	ds_read_b128 v[114:117], v219 offset:49664
	ds_read_b128 v[118:121], v219 offset:49920
	s_waitcnt lgkmcnt(4)
	v_mfma_f32_16x16x32_bf16 v[42:45], v[122:125], v[94:97], v[42:45]
	v_mfma_f32_16x16x32_bf16 v[46:49], v[126:129], v[94:97], v[46:49]
	v_mfma_f32_16x16x32_bf16 v[50:53], v[58:61], v[94:97], v[50:53]
	v_mfma_f32_16x16x32_bf16 v[54:57], v[62:65], v[94:97], v[54:57]
	s_waitcnt vmcnt(0)
	s_barrier
	ds_read_b128 v[122:125], v219 offset:57344
	ds_read_b128 v[126:129], v219 offset:57600
	ds_read_b128 v[58:61], v219 offset:57856
	ds_read_b128 v[62:65], v219 offset:58112
	s_waitcnt lgkmcnt(4)
	v_mfma_f32_16x16x32_bf16 v[22:25], v[106:109], v[102:105], v[22:25]
	v_mfma_f32_16x16x32_bf16 v[30:33], v[110:113], v[102:105], v[30:33]
	v_mfma_f32_16x16x32_bf16 v[34:37], v[114:117], v[102:105], v[34:37]
	v_mfma_f32_16x16x32_bf16 v[38:41], v[118:121], v[102:105], v[38:41]
	s_waitcnt vmcnt(1)
	s_barrier
	s_waitcnt lgkmcnt(0)
	v_mfma_f32_16x16x32_bf16 v[42:45], v[122:125], v[102:105], v[42:45]
	v_mfma_f32_16x16x32_bf16 v[46:49], v[126:129], v[102:105], v[46:49]
	v_mfma_f32_16x16x32_bf16 v[50:53], v[58:61], v[102:105], v[50:53]
	v_mfma_f32_16x16x32_bf16 v[54:57], v[62:65], v[102:105], v[54:57]
	s_cmp_eq_u32 s73, 0
	s_cbranch_scc1 .Lrg_v_A_end
	s_waitcnt vmcnt(0)
	s_barrier

; #define ATT_VLOAD(buf, p) do { const bf16_t* vp_ = vloc + (size_t)((p) * 8 * NH) * 1024; \
;         _Pragma("unroll") for (int df = 0; df < 8; ++df) va[buf][df] = *(const bf16x8*)(vp_ + df * 128); } while (0)
; template <bool LOCAL>
; __device__ __forceinline__ void attn_unit(const bf16_t* Q, const bf16_t* KT, const bf16_t* VT, bf16_t* O, LAS unsigned char* lds, int b, int h, int r, int w, int tq, int lane) {
;     ...
;     if (LOCAL) {
;         const bf16_t* vloc = VT + ((size_t)(((rgl >> 3) + g) * NH + h)) * 1024 + q * 8;
;         bf16x8 va[2][8];
;     ...
;         ATT_VLOAD(0, 0);
; #pragma unroll
;         for (int p = 0; p < 8; ++p) {
;             __builtin_amdgcn_s_barrier();
;             if (p + 1 < 8) ATT_VLOAD((p + 1) & 1, p + 1);
;             __builtin_amdgcn_sched_barrier(0);
; #pragma unroll
;             for (int df = 0; df < 8; ++df) o[df] = __builtin_amdgcn_mfma_f32_16x16x32_bf16(va[p & 1][df], pb[p], o[df], 0, 0, 0);
;             __builtin_amdgcn_sched_barrier(0);
;         }
;     ...
;     }
.Lrg_v_B:
	s_waitcnt vmcnt(6)
	s_barrier
	s_waitcnt vmcnt(5)
	s_barrier
	s_add_i32 m0, s59, 57344
	v_add_co_u32_e32 v222, vcc, s2, v226
	s_nop 1
	v_addc_co_u32_e32 v223, vcc, 0, v227, vcc
	global_load_lds_dwordx4 v[222:223], off
	s_waitcnt vmcnt(5)
	s_barrier
	ds_read_b128 v[106:109], v219 offset:16384
	ds_read_b128 v[110:113], v219 offset:16640
	ds_read_b128 v[114:117], v219 offset:16896
	ds_read_b128 v[118:121], v219 offset:17152
	s_add_i32 m0, s59, 0
	v_add_co_u32_e32 v222, vcc, s60, v220
	s_nop 1
	v_addc_co_u32_e32 v223, vcc, 0, v221, vcc
	global_load_lds_dwordx4 v[222:223], off
	s_waitcnt vmcnt(5)
	s_barrier
	ds_read_b128 v[122:125], v219 offset:24576
	ds_read_b128 v[126:129], v219 offset:24832
	ds_read_b128 v[58:61], v219 offset:25088
	ds_read_b128 v[62:65], v219 offset:25344
	s_waitcnt lgkmcnt(4)
	v_mfma_f32_16x16x32_bf16 v[22:25], v[106:109], v[66:69], 0
	v_mfma_f32_16x16x32_bf16 v[30:33], v[110:113], v[66:69], 0
	v_mfma_f32_16x16x32_bf16 v[34:37], v[114:117], v[66:69], 0
	v_mfma_f32_16x16x32_bf16 v[38:41], v[118:121], v[66:69], 0
	s_add_i32 m0, s59, 8192
	v_add_co_u32_e32 v222, vcc, s60, v226
	s_nop 1
	v_addc_co_u32_e32 v223, vcc, 0, v227, vcc
	global_load_lds_dwordx4 v[222:223], off
	s_waitcnt vmcnt(5)
	s_barrier
	ds_read_b128 v[106:109], v219 offset:32768
	ds_read_b128 v[110:113], v219 offset:33024
	ds_read_b128 v[114:117], v219 offset:33280
	ds_read_b128 v[118:121], v219 offset:33536
	s_waitcnt lgkmcnt(4)
	v_mfma_f32_16x16x32_bf16 v[42:45], v[122:125], v[66:69], 0
	v_mfma_f32_16x16x32_bf16 v[46:49], v[126:129], v[66:69], 0
	v_mfma_f32_16x16x32_bf16 v[50:53], v[58:61], v[66:69], 0
	v_mfma_f32_16x16x32_bf16 v[54:57], v[62:65], v[66:69], 0
	s_add_i32 m0, s59, 16384
	v_add_co_u32_e32 v222, vcc, s61, v220
	s_nop 1
	v_addc_co_u32_e32 v223, vcc, 0, v221, vcc
	global_load_lds_dwordx4 v[222:223], off
	s_waitcnt vmcnt(5)
	s_barrier
	ds_read_b128 v[122:125], v219 offset:40960
	ds_read_b128 v[126:129], v219 offset:41216
	ds_read_b128 v[58:61], v219 offset:41472
	ds_read_b128 v[62:65], v219 offset:41728
	s_waitcnt lgkmcnt(4)
	v_mfma_f32_16x16x32_bf16 v[22:25], v[106:109], v[70:73], v[22:25]
	v_mfma_f32_16x16x32_bf16 v[30:33], v[110:113], v[70:73], v[30:33]
	v_mfma_f32_16x16x32_bf16 v[34:37], v[114:117], v[70:73], v[34:37]
	v_mfma_f32_16x16x32_bf16 v[38:41], v[118:121], v[70:73], v[38:41]
	s_add_i32 m0, s59, 24576
	v_add_co_u32_e32 v222, vcc, s61, v226
	s_nop 1
	v_addc_co_u32_e32 v223, vcc, 0, v227, vcc
	global_load_lds_dwordx4 v[222:223], off
	s_waitcnt vmcnt(5)
	s_barrier
	ds_read_b128 v[106:109], v219 offset:49152
	ds_read_b128 v[110:113], v219 offset:49408
	ds_read_b128 v[114:117], v219 offset:49664
	ds_read_b128 v[118:121], v219 offset:49920
	s_waitcnt lgkmcnt(4)
	v_mfma_f32_16x16x32_bf16 v[42:45], v[122:125], v[70:73], v[42:45]
	v_mfma_f32_16x16x32_bf16 v[46:49], v[126:129], v[70:73], v[46:49]
	v_mfma_f32_16x16x32_bf16 v[50:53], v[58:61], v[70:73], v[50:53]
	v_mfma_f32_16x16x32_bf16 v[54:57], v[62:65], v[70:73], v[54:57]
	s_add_i32 m0, s59, 32768
	v_add_co_u32_e32 v222, vcc, s17, v220
	s_nop 1
	v_addc_co_u32_e32 v223, vcc, 0, v221, vcc
	global_load_lds_dwordx4 v[222:223], off
	s_waitcnt vmcnt(5)
	s_barrier
	ds_read_b128 v[122:125], v219 offset:57344
	ds_read_b128 v[126:129], v219 offset:57600
	ds_read_b128 v[58:61], v219 offset:57856
	ds_read_b128 v[62:65], v219 offset:58112
	s_waitcnt lgkmcnt(4)
	v_mfma_f32_16x16x32_bf16 v[22:25], v[106:109], v[74:77], v[22:25]
	v_mfma_f32_16x16x32_bf16 v[30:33], v[110:113], v[74:77], v[30:33]
	v_mfma_f32_16x16x32_bf16 v[34:37], v[114:117], v[74:77], v[34:37]
	v_mfma_f32_16x16x32_bf16 v[38:41], v[118:121], v[74:77], v[38:41]
	s_add_i32 m0, s59, 40960
	v_add_co_u32_e32 v222, vcc, s17, v226
	s_nop 1
	v_addc_co_u32_e32 v223, vcc, 0, v227, vcc
	global_load_lds_dwordx4 v[222:223], off
	s_waitcnt vmcnt(5)
	s_barrier
	ds_read_b128 v[106:109], v219 offset:0
	ds_read_b128 v[110:113], v219 offset:256
	ds_read_b128 v[114:117], v219 offset:512
	ds_read_b128 v[118:121], v219 offset:768
	s_waitcnt lgkmcnt(4)
	v_mfma_f32_16x16x32_bf16 v[42:45], v[122:125], v[74:77], v[42:45]
	v_mfma_f32_16x16x32_bf16 v[46:49], v[126:129], v[74:77], v[46:49]
	v_mfma_f32_16x16x32_bf16 v[50:53], v[58:61], v[74:77], v[50:53]
	v_mfma_f32_16x16x32_bf16 v[54:57], v[62:65], v[74:77], v[54:57]
	s_add_i32 m0, s59, 49152
	v_add_co_u32_e32 v222, vcc, s62, v220
	s_nop 1
	v_addc_co_u32_e32 v223, vcc, 0, v221, vcc
	global_load_lds_dwordx4 v[222:223], off
	s_waitcnt vmcnt(5)
	s_barrier
	ds_read_b128 v[122:125], v219 offset:8192
	ds_read_b128 v[126:129], v219 offset:8448
	ds_read_b128 v[58:61], v219 offset:8704
	ds_read_b128 v[62:65], v219 offset:8960
	s_waitcnt lgkmcnt(4)
	v_mfma_f32_16x16x32_bf16 v[22:25], v[106:109], v[78:81], v[22:25]
	v_mfma_f32_16x16x32_bf16 v[30:33], v[110:113], v[78:81], v[30:33]
	v_mfma_f32_16x16x32_bf16 v[34:37], v[114:117], v[78:81], v[34:37]
	v_mfma_f32_16x16x32_bf16 v[38:41], v[118:121], v[78:81], v[38:41]
	s_add_i32 m0, s59, 57344
	v_add_co_u32_e32 v222, vcc, s62, v226
	s_nop 1
	v_addc_co_u32_e32 v223, vcc, 0, v227, vcc
	global_load_lds_dwordx4 v[222:223], off
	s_waitcnt vmcnt(5)
	s_barrier
	ds_read_b128 v[106:109], v219 offset:16384
	ds_read_b128 v[110:113], v219 offset:16640
	ds_read_b128 v[114:117], v219 offset:16896
	ds_read_b128 v[118:121], v219 offset:17152
	s_waitcnt lgkmcnt(4)
	v_mfma_f32_16x16x32_bf16 v[42:45], v[122:125], v[78:81], v[42:45]
	v_mfma_f32_16x16x32_bf16 v[46:49], v[126:129], v[78:81], v[46:49]
	v_mfma_f32_16x16x32_bf16 v[50:53], v[58:61], v[78:81], v[50:53]
	v_mfma_f32_16x16x32_bf16 v[54:57], v[62:65], v[78:81], v[54:57]
	s_cmp_eq_u32 s73, 0
	s_cbranch_scc1 .Lrg_v_B_nd9
	s_add_i32 m0, s59, 0
	v_add_co_u32_e32 v222, vcc, s75, v220
	s_nop 1
	v_addc_co_u32_e32 v223, vcc, 0, v221, vcc
	global_load_lds_dwordx4 v[222:223], off
; #define ATT_VLOAD(buf, p) do { const bf16_t* vp_ = vloc + (size_t)((p) * 8 * NH) * 1024; \
;         _Pragma("unroll") for (int df = 0; df < 8; ++df) va[buf][df] = *(const bf16x8*)(vp_ + df * 128); } while (0)
; template <bool LOCAL>
; __device__ __forceinline__ void attn_unit(const bf16_t* Q, const bf16_t* KT, const bf16_t* VT, bf16_t* O, LAS unsigned char* lds, int b, int h, int r, int w, int tq, int lane) {
;     ...
;     if (LOCAL) {
;         const bf16_t* vloc = VT + ((size_t)(((rgl >> 3) + g) * NH + h)) * 1024 + q * 8;
;         bf16x8 va[2][8];
;     ...
;         ATT_VLOAD(0, 0);
; #pragma unroll
;         for (int p = 0; p < 8; ++p) {
;             __builtin_amdgcn_s_barrier();
;             if (p + 1 < 8) ATT_VLOAD((p + 1) & 1, p + 1);
;             __builtin_amdgcn_sched_barrier(0);
; #pragma unroll
;             for (int df = 0; df < 8; ++df) o[df] = __builtin_amdgcn_mfma_f32_16x16x32_bf16(va[p & 1][df], pb[p], o[df], 0, 0, 0);
;             __builtin_amdgcn_sched_barrier(0);
;         }
;     ...
;     }
.Lrg_v_B_nd9:
	s_waitcnt vmcnt(4)
	s_barrier
	ds_read_b128 v[122:125], v219 offset:24576
	ds_read_b128 v[126:129], v219 offset:24832
	ds_read_b128 v[58:61], v219 offset:25088
	ds_read_b128 v[62:65], v219 offset:25344
	s_waitcnt lgkmcnt(4)
	v_mfma_f32_16x16x32_bf16 v[22:25], v[106:109], v[82:85], v[22:25]
	v_mfma_f32_16x16x32_bf16 v[30:33], v[110:113], v[82:85], v[30:33]
	v_mfma_f32_16x16x32_bf16 v[34:37], v[114:117], v[82:85], v[34:37]
	v_mfma_f32_16x16x32_bf16 v[38:41], v[118:121], v[82:85], v[38:41]
	s_cmp_eq_u32 s73, 0
	s_cbranch_scc1 .Lrg_v_B_nd10
	s_add_i32 m0, s59, 8192
	v_add_co_u32_e32 v222, vcc, s75, v226
	s_nop 1
	v_addc_co_u32_e32 v223, vcc, 0, v227, vcc
	global_load_lds_dwordx4 v[222:223], off
.Lrg_v_B_nd10:
	s_waitcnt vmcnt(3)
	s_barrier
	ds_read_b128 v[106:109], v219 offset:32768
	ds_read_b128 v[110:113], v219 offset:33024
	ds_read_b128 v[114:117], v219 offset:33280
	ds_read_b128 v[118:121], v219 offset:33536
	s_waitcnt lgkmcnt(4)
	v_mfma_f32_16x16x32_bf16 v[42:45], v[122:125], v[82:85], v[42:45]
	v_mfma_f32_16x16x32_bf16 v[46:49], v[126:129], v[82:85], v[46:49]
	v_mfma_f32_16x16x32_bf16 v[50:53], v[58:61], v[82:85], v[50:53]
	v_mfma_f32_16x16x32_bf16 v[54:57], v[62:65], v[82:85], v[54:57]
	s_waitcnt vmcnt(2)
	s_barrier
	ds_read_b128 v[122:125], v219 offset:40960
	ds_read_b128 v[126:129], v219 offset:41216
	ds_read_b128 v[58:61], v219 offset:41472
	ds_read_b128 v[62:65], v219 offset:41728
	s_waitcnt lgkmcnt(4)
	v_mfma_f32_16x16x32_bf16 v[22:25], v[106:109], v[86:89], v[22:25]
	v_mfma_f32_16x16x32_bf16 v[30:33], v[110:113], v[86:89], v[30:33]
	v_mfma_f32_16x16x32_bf16 v[34:37], v[114:117], v[86:89], v[34:37]
	v_mfma_f32_16x16x32_bf16 v[38:41], v[118:121], v[86:89], v[38:41]
	s_waitcnt vmcnt(1)
	s_barrier
	ds_read_b128 v[106:109], v219 offset:49152
	ds_read_b128 v[110:113], v219 offset:49408
	ds_read_b128 v[114:117], v219 offset:49664
	ds_read_b128 v[118:121], v219 offset:49920
	s_waitcnt lgkmcnt(4)
	v_mfma_f32_16x16x32_bf16 v[42:45], v[122:125], v[86:89], v[42:45]
	v_mfma_f32_16x16x32_bf16 v[46:49], v[126:129], v[86:89], v[46:49]
	v_mfma_f32_16x16x32_bf16 v[50:53], v[58:61], v[86:89], v[50:53]
	v_mfma_f32_16x16x32_bf16 v[54:57], v[62:65], v[86:89], v[54:57]
	s_waitcnt vmcnt(0)
	s_barrier
	ds_read_b128 v[122:125], v219 offset:57344
	ds_read_b128 v[126:129], v219 offset:57600
	ds_read_b128 v[58:61], v219 offset:57856
	ds_read_b128 v[62:65], v219 offset:58112
	s_waitcnt lgkmcnt(4)
	v_mfma_f32_16x16x32_bf16 v[22:25], v[106:109], v[94:97], v[22:25]
	v_mfma_f32_16x16x32_bf16 v[30:33], v[110:113], v[94:97], v[30:33]
	v_mfma_f32_16x16x32_bf16 v[34:37], v[114:117], v[94:97], v[34:37]
	v_mfma_f32_16x16x32_bf16 v[38:41], v[118:121], v[94:97], v[38:41]
	s_waitcnt vmcnt(1)
	s_barrier
	ds_read_b128 v[106:109], v219 offset:0
	ds_read_b128 v[110:113], v219 offset:256
	ds_read_b128 v[114:117], v219 offset:512
	ds_read_b128 v[118:121], v219 offset:768
	s_waitcnt lgkmcnt(4)
	v_mfma_f32_16x16x32_bf16 v[42:45], v[122:125], v[94:97], v[42:45]
	v_mfma_f32_16x16x32_bf16 v[46:49], v[126:129], v[94:97], v[46:49]
	v_mfma_f32_16x16x32_bf16 v[50:53], v[58:61], v[94:97], v[50:53]
	v_mfma_f32_16x16x32_bf16 v[54:57], v[62:65], v[94:97], v[54:57]
	s_cmp_eq_u32 s73, 0
	s_cbranch_scc1 .Lrg_v_B_end
	s_waitcnt vmcnt(0)
	s_barrier
	ds_read_b128 v[122:125], v219 offset:8192
	ds_read_b128 v[126:129], v219 offset:8448
	ds_read_b128 v[58:61], v219 offset:8704
	ds_read_b128 v[62:65], v219 offset:8960
	s_waitcnt lgkmcnt(4)
	v_mfma_f32_16x16x32_bf16 v[22:25], v[106:109], v[102:105], v[22:25]
	v_mfma_f32_16x16x32_bf16 v[30:33], v[110:113], v[102:105], v[30:33]
	v_mfma_f32_16x16x32_bf16 v[34:37], v[114:117], v[102:105], v[34:37]
	v_mfma_f32_16x16x32_bf16 v[38:41], v[118:121], v[102:105], v[38:41]
	s_waitcnt lgkmcnt(0)
	v_mfma_f32_16x16x32_bf16 v[42:45], v[122:125], v[102:105], v[42:45]
	v_mfma_f32_16x16x32_bf16 v[46:49], v[126:129], v[102:105], v[46:49]
	v_mfma_f32_16x16x32_bf16 v[50:53], v[58:61], v[102:105], v[50:53]
	v_mfma_f32_16x16x32_bf16 v[54:57], v[62:65], v[102:105], v[54:57]

; #define ATT_KLOAD(buf, p) do { const bf16_t* kp_ = kloc + (size_t)((p) * 8 * NH) * 1024; \
;         _Pragma("unroll") for (int f = 0; f < 2; ++f) _Pragma("unroll") for (int ks = 0; ks < 4; ++ks) ka[buf][f * 4 + ks] = *(const bf16x8*)(kp_ + f * 128 + ks * 256); } while (0)
; template <bool LOCAL>
; __device__ __forceinline__ void attn_unit(const bf16_t* Q, const bf16_t* KT, const bf16_t* VT, bf16_t* O, LAS unsigned char* lds, int b, int h, int r, int w, int tq, int lane) {
;     ...
;     bf16x8 bq[4];
;     { const bf16_t* qp = Q + (size_t)qrow * D + h * HD + 8 * g;
; #pragma unroll
;       for (int ks = 0; ks < 4; ++ks) bq[ks] = *(const bf16x8*)(qp + 32 * ks); }
;     constexpr int NP = LOCAL ? 16 : 8, CP = LOCAL ? 8 : 0;
;     f32x4 s[2 * NP];
;     int rs = 0, ws = 0;
;     if (LOCAL) { rs = r - 4; rs = rs < 0 ? 0 : (rs > 24 ? 24 : rs); ws = 16 * w - 8; ws = ws < 0 ? 0 : (ws > 32 ? 32 : ws); }
;     const int rgl = b * SEQ + rs * GRID_W + ws;
;     if (LOCAL) {
;         const bf16_t* kloc = KT + ((size_t)(((rgl >> 3) + (q >> 2)) * NH + h)) * 1024 + (q & 3) * 32 + g * 8;
;         bf16x8 ka[2][8];
;     ...
;         ATT_KLOAD(0, 0);
; #pragma unroll
;         for (int p = 0; p < 8; ++p) {
;             __builtin_amdgcn_s_barrier();
;             if (p + 1 < 8) ATT_KLOAD((p + 1) & 1, p + 1);
;             __builtin_amdgcn_sched_barrier(0);
; #pragma unroll
;             for (int f = 0; f < 2; ++f) { f32x4 a = {0.f, 0.f, 0.f, 0.f};
; #pragma unroll
;                 for (int ks = 0; ks < 4; ++ks) a = __builtin_amdgcn_mfma_f32_16x16x32_bf16(ka[p & 1][f * 4 + ks], bq[ks], a, 0, 0, 0);
;                 s[2 * p + f] = a; }
;             __builtin_amdgcn_sched_barrier(0);
;         }
;     ...
;     }
.LBB9_674:
	v_ashrrev_i32_e32 v163, 31, v162
	v_lshlrev_b64 v[2:3], 12, v[162:163]
	s_mov_b32 s4, s52
	v_lshl_add_u64 v[2:3], v[158:159], 0, v[2:3]
	global_load_dwordx4 v[138:141], v[2:3], off
	global_load_dwordx4 v[134:137], v[2:3], off offset:64
	global_load_dwordx4 v[130:133], v[2:3], off offset:128
	global_load_dwordx4 v[62:65], v[2:3], off offset:192
	v_med3_i32 v2, s4, 4, 28
	v_lshlrev_b32_e32 v2, 6, v2
	v_add_u32_e32 v2, v2, v157
	v_add_u32_e32 v2, 0xffffff00, v2
	v_ashrrev_i32_e32 v194, 3, v2
	v_add_u32_e32 v2, v194, v168
	v_lshl_or_b32 v2, v2, 4, s72
	v_ashrrev_i32_e32 v3, 31, v2
	v_lshlrev_b64 v[2:3], 11, v[2:3]
	v_lshl_add_u64 v[70:71], v[146:147], 0, v[2:3]
	v_med3_i32 v232, s52, 4, 28
	v_add_u32_e32 v195, s51, v232
	s_lshr_b32 s54, s57, 2
	s_sub_i32 s54, s52, s54
	s_add_i32 s55, s54, -4
	s_max_i32 s55, s55, 0
	s_min_i32 s55, s55, 24
	s_add_i32 s73, s54, -3
	s_max_i32 s73, s73, 0
	s_min_i32 s73, s73, 24
	s_sub_i32 s73, s73, s55
	s_lshr_b32 s54, s57, 2
	s_mul_i32 s53, s73, s54
	s_ashr_i32 s54, s70, 6
	s_lshl_b32 s54, s54, 8
	s_lshl_b32 s55, s55, 3
	s_add_i32 s54, s54, s55
	s_add_i32 s54, s54, s57
	s_lshl_b32 s54, s54, 15
	s_lshl_b32 s55, s72, 11
	s_add_i32 s28, s54, s55
	s_mov_b32 s75, 0x200000
	s_lshl_b32 s54, s57, 10
	s_add_i32 s59, s54, 0x10000
	s_and_b32 s54, s57, 1
	s_lshl_b32 s54, s54, 1
	v_xor_b32_e32 v218, s54, v164
	v_lshlrev_b32_e32 v218, 4, v218
	v_add_u32_e32 v218, s28, v218
	ds_read_b64 v[220:221], v241 offset:192
	s_waitcnt lgkmcnt(0)
	v_add_co_u32_e32 v220, vcc, 0x21f00000, v220
	s_nop 1
	v_addc_co_u32_e32 v221, vcc, 0, v221, vcc
	v_add_co_u32_e32 v220, vcc, v220, v218
	s_nop 1
	v_addc_co_u32_e32 v221, vcc, 0, v221, vcc
	v_add_co_u32_e32 v226, vcc, 0x400, v220
	s_nop 1
	v_addc_co_u32_e32 v227, vcc, 0, v221, vcc
	s_and_b32 s55, s57, 3
	s_lshl_b32 s55, s55, 1
	s_add_i32 s55, s55, -1
	s_max_i32 s55, s55, 0
	s_min_i32 s55, s55, 4
	v_lshrrev_b32_e32 v219, 2, v166
	v_add_u32_e32 v219, s55, v219
	v_and_b32_e32 v224, 3, v166
	v_lshl_or_b32 v224, v224, 2, v165
	v_and_b32_e32 v225, 1, v219
	v_lshlrev_b32_e32 v225, 1, v225
	v_xor_b32_e32 v224, v224, v225
	v_lshlrev_b32_e32 v224, 4, v224
	v_lshl_add_u32 v219, v219, 10, v224
	v_add_u32_e32 v219, 0x10000, v219
	s_add_i32 m0, s59, 0
	s_nop 0
	global_load_lds_dwordx4 v[220:221], off
	s_add_i32 m0, s59, 8192
	s_nop 0
	global_load_lds_dwordx4 v[226:227], off
	s_add_i32 m0, s59, 16384
	v_add_co_u32_e32 v222, vcc, s6, v220
	s_nop 1
	v_addc_co_u32_e32 v223, vcc, 0, v221, vcc
	global_load_lds_dwordx4 v[222:223], off
	s_add_i32 m0, s59, 24576
	v_add_co_u32_e32 v222, vcc, s6, v226
	s_nop 1
	v_addc_co_u32_e32 v223, vcc, 0, v227, vcc
	global_load_lds_dwordx4 v[222:223], off
	s_add_i32 m0, s59, 32768
	v_add_co_u32_e32 v222, vcc, s7, v220
	s_nop 1
	v_addc_co_u32_e32 v223, vcc, 0, v221, vcc
	global_load_lds_dwordx4 v[222:223], off
	s_add_i32 m0, s59, 40960
	v_add_co_u32_e32 v222, vcc, s7, v226
	s_nop 1
	v_addc_co_u32_e32 v223, vcc, 0, v227, vcc
	global_load_lds_dwordx4 v[222:223], off
	s_add_i32 m0, s59, 49152
	v_add_co_u32_e32 v222, vcc, s2, v220
	s_nop 1
	v_addc_co_u32_e32 v223, vcc, 0, v221, vcc
	global_load_lds_dwordx4 v[222:223], off
	s_cmp_eq_u32 s53, 0
	s_cbranch_scc0 .Lrg_k_B
	s_waitcnt vmcnt(6)
	s_barrier
	ds_read_b128 v[2:5], v219 offset:0
	ds_read_b128 v[6:9], v219 offset:256
	ds_read_b128 v[10:13], v219 offset:512
	ds_read_b128 v[14:17], v219 offset:768
	s_waitcnt vmcnt(5)
	s_barrier
	ds_read_b128 v[18:21], v219 offset:8192
	ds_read_b128 v[22:25], v219 offset:8448
	ds_read_b128 v[26:29], v219 offset:8704
	ds_read_b128 v[30:33], v219 offset:8960
	s_waitcnt lgkmcnt(4)
	v_mfma_f32_16x16x32_bf16 v[126:129], v[2:5], v[138:141], 0
	v_mfma_f32_16x16x32_bf16 v[122:125], v[6:9], v[138:141], 0
	v_mfma_f32_16x16x32_bf16 v[126:129], v[10:13], v[134:137], v[126:129]
	v_mfma_f32_16x16x32_bf16 v[122:125], v[14:17], v[134:137], v[122:125]
	s_add_i32 m0, s59, 57344
	v_add_co_u32_e32 v222, vcc, s2, v226
	s_nop 1
	v_addc_co_u32_e32 v223, vcc, 0, v227, vcc
	global_load_lds_dwordx4 v[222:223], off
	s_waitcnt vmcnt(5)
	s_barrier
	ds_read_b128 v[2:5], v219 offset:16384
	ds_read_b128 v[6:9], v219 offset:16640
	ds_read_b128 v[10:13], v219 offset:16896
	ds_read_b128 v[14:17], v219 offset:17152
	s_waitcnt lgkmcnt(4)
	v_mfma_f32_16x16x32_bf16 v[126:129], v[18:21], v[130:133], v[126:129]
	v_mfma_f32_16x16x32_bf16 v[122:125], v[22:25], v[130:133], v[122:125]
	v_mfma_f32_16x16x32_bf16 v[126:129], v[26:29], v[62:65], v[126:129]
	v_mfma_f32_16x16x32_bf16 v[122:125], v[30:33], v[62:65], v[122:125]
	s_add_i32 m0, s59, 0
	v_add_co_u32_e32 v222, vcc, s60, v220
	s_nop 1
	v_addc_co_u32_e32 v223, vcc, 0, v221, vcc
	global_load_lds_dwordx4 v[222:223], off
	s_waitcnt vmcnt(5)
	s_barrier
	ds_read_b128 v[18:21], v219 offset:24576
	ds_read_b128 v[22:25], v219 offset:24832
	ds_read_b128 v[26:29], v219 offset:25088
	ds_read_b128 v[30:33], v219 offset:25344
	s_waitcnt lgkmcnt(4)
	v_mfma_f32_16x16x32_bf16 v[118:121], v[2:5], v[138:141], 0
	v_mfma_f32_16x16x32_bf16 v[114:117], v[6:9], v[138:141], 0
	v_mfma_f32_16x16x32_bf16 v[118:121], v[10:13], v[134:137], v[118:121]
	v_mfma_f32_16x16x32_bf16 v[114:117], v[14:17], v[134:137], v[114:117]
	s_add_i32 m0, s59, 8192
	v_add_co_u32_e32 v222, vcc, s60, v226
	s_nop 1
	v_addc_co_u32_e32 v223, vcc, 0, v227, vcc
	global_load_lds_dwordx4 v[222:223], off
	s_waitcnt vmcnt(5)
	s_barrier
; #define ATT_KLOAD(buf, p) do { const bf16_t* kp_ = kloc + (size_t)((p) * 8 * NH) * 1024; \
;         _Pragma("unroll") for (int f = 0; f < 2; ++f) _Pragma("unroll") for (int ks = 0; ks < 4; ++ks) ka[buf][f * 4 + ks] = *(const bf16x8*)(kp_ + f * 128 + ks * 256); } while (0)
; template <bool LOCAL>
; __device__ __forceinline__ void attn_unit(const bf16_t* Q, const bf16_t* KT, const bf16_t* VT, bf16_t* O, LAS unsigned char* lds, int b, int h, int r, int w, int tq, int lane) {
;     ...
;     if (LOCAL) {
;         const bf16_t* kloc = KT + ((size_t)(((rgl >> 3) + (q >> 2)) * NH + h)) * 1024 + (q & 3) * 32 + g * 8;
;         bf16x8 ka[2][8];
;     ...
;         ATT_KLOAD(0, 0);
; #pragma unroll
;         for (int p = 0; p < 8; ++p) {
;             __builtin_amdgcn_s_barrier();
;             if (p + 1 < 8) ATT_KLOAD((p + 1) & 1, p + 1);
;             __builtin_amdgcn_sched_barrier(0);
; #pragma unroll
;             for (int f = 0; f < 2; ++f) { f32x4 a = {0.f, 0.f, 0.f, 0.f};
; #pragma unroll
;                 for (int ks = 0; ks < 4; ++ks) a = __builtin_amdgcn_mfma_f32_16x16x32_bf16(ka[p & 1][f * 4 + ks], bq[ks], a, 0, 0, 0);
;                 s[2 * p + f] = a; }
;             __builtin_amdgcn_sched_barrier(0);
;         }
;     ...
;     }
	ds_read_b128 v[2:5], v219 offset:32768
	ds_read_b128 v[6:9], v219 offset:33024
	ds_read_b128 v[10:13], v219 offset:33280
	ds_read_b128 v[14:17], v219 offset:33536
	s_waitcnt lgkmcnt(4)
	v_mfma_f32_16x16x32_bf16 v[118:121], v[18:21], v[130:133], v[118:121]
	v_mfma_f32_16x16x32_bf16 v[114:117], v[22:25], v[130:133], v[114:117]
	v_mfma_f32_16x16x32_bf16 v[118:121], v[26:29], v[62:65], v[118:121]
	v_mfma_f32_16x16x32_bf16 v[114:117], v[30:33], v[62:65], v[114:117]
	s_add_i32 m0, s59, 16384
	v_add_co_u32_e32 v222, vcc, s61, v220
	s_nop 1
	v_addc_co_u32_e32 v223, vcc, 0, v221, vcc
	global_load_lds_dwordx4 v[222:223], off
	s_waitcnt vmcnt(5)
	s_barrier
	ds_read_b128 v[18:21], v219 offset:40960
	ds_read_b128 v[22:25], v219 offset:41216
	ds_read_b128 v[26:29], v219 offset:41472
	ds_read_b128 v[30:33], v219 offset:41728
	s_waitcnt lgkmcnt(4)
	v_mfma_f32_16x16x32_bf16 v[110:113], v[2:5], v[138:141], 0
	v_mfma_f32_16x16x32_bf16 v[106:109], v[6:9], v[138:141], 0
	v_mfma_f32_16x16x32_bf16 v[110:113], v[10:13], v[134:137], v[110:113]
	v_mfma_f32_16x16x32_bf16 v[106:109], v[14:17], v[134:137], v[106:109]
	s_add_i32 m0, s59, 24576
	v_add_co_u32_e32 v222, vcc, s61, v226
	s_nop 1
	v_addc_co_u32_e32 v223, vcc, 0, v227, vcc
	global_load_lds_dwordx4 v[222:223], off
	s_waitcnt vmcnt(5)
	s_barrier
	ds_read_b128 v[2:5], v219 offset:49152
	ds_read_b128 v[6:9], v219 offset:49408
	ds_read_b128 v[10:13], v219 offset:49664
	ds_read_b128 v[14:17], v219 offset:49920
	s_waitcnt lgkmcnt(4)
	v_mfma_f32_16x16x32_bf16 v[110:113], v[18:21], v[130:133], v[110:113]
	v_mfma_f32_16x16x32_bf16 v[106:109], v[22:25], v[130:133], v[106:109]
	v_mfma_f32_16x16x32_bf16 v[110:113], v[26:29], v[62:65], v[110:113]
	v_mfma_f32_16x16x32_bf16 v[106:109], v[30:33], v[62:65], v[106:109]
	s_add_i32 m0, s59, 32768
	v_add_co_u32_e32 v222, vcc, s17, v220
	s_nop 1
	v_addc_co_u32_e32 v223, vcc, 0, v221, vcc
	global_load_lds_dwordx4 v[222:223], off
	s_waitcnt vmcnt(5)
	s_barrier
	ds_read_b128 v[18:21], v219 offset:57344
	ds_read_b128 v[22:25], v219 offset:57600
	ds_read_b128 v[26:29], v219 offset:57856
	ds_read_b128 v[30:33], v219 offset:58112
	s_waitcnt lgkmcnt(4)
	v_mfma_f32_16x16x32_bf16 v[102:105], v[2:5], v[138:141], 0
	v_mfma_f32_16x16x32_bf16 v[98:101], v[6:9], v[138:141], 0
	v_mfma_f32_16x16x32_bf16 v[102:105], v[10:13], v[134:137], v[102:105]
	v_mfma_f32_16x16x32_bf16 v[98:101], v[14:17], v[134:137], v[98:101]
	s_add_i32 m0, s59, 40960
	v_add_co_u32_e32 v222, vcc, s17, v226
	s_nop 1
	v_addc_co_u32_e32 v223, vcc, 0, v227, vcc
	global_load_lds_dwordx4 v[222:223], off
	s_waitcnt vmcnt(5)
	s_barrier
	ds_read_b128 v[2:5], v219 offset:0
	ds_read_b128 v[6:9], v219 offset:256
	ds_read_b128 v[10:13], v219 offset:512
	ds_read_b128 v[14:17], v219 offset:768
	s_waitcnt lgkmcnt(4)
	v_mfma_f32_16x16x32_bf16 v[102:105], v[18:21], v[130:133], v[102:105]
	v_mfma_f32_16x16x32_bf16 v[98:101], v[22:25], v[130:133], v[98:101]
	v_mfma_f32_16x16x32_bf16 v[102:105], v[26:29], v[62:65], v[102:105]
	v_mfma_f32_16x16x32_bf16 v[98:101], v[30:33], v[62:65], v[98:101]
	s_add_i32 m0, s59, 49152
	v_add_co_u32_e32 v222, vcc, s62, v220
	s_nop 1
	v_addc_co_u32_e32 v223, vcc, 0, v221, vcc
	global_load_lds_dwordx4 v[222:223], off
	s_waitcnt vmcnt(5)
	s_barrier
	ds_read_b128 v[18:21], v219 offset:8192
	ds_read_b128 v[22:25], v219 offset:8448
	ds_read_b128 v[26:29], v219 offset:8704
	ds_read_b128 v[30:33], v219 offset:8960
	s_waitcnt lgkmcnt(4)
	v_mfma_f32_16x16x32_bf16 v[94:97], v[2:5], v[138:141], 0
	v_mfma_f32_16x16x32_bf16 v[90:93], v[6:9], v[138:141], 0
	v_mfma_f32_16x16x32_bf16 v[94:97], v[10:13], v[134:137], v[94:97]
	v_mfma_f32_16x16x32_bf16 v[90:93], v[14:17], v[134:137], v[90:93]
	s_add_i32 m0, s59, 57344
	v_add_co_u32_e32 v222, vcc, s62, v226
	s_nop 1
	v_addc_co_u32_e32 v223, vcc, 0, v227, vcc
	global_load_lds_dwordx4 v[222:223], off
	s_waitcnt vmcnt(5)
	s_barrier
	ds_read_b128 v[2:5], v219 offset:16384
	ds_read_b128 v[6:9], v219 offset:16640
	ds_read_b128 v[10:13], v219 offset:16896
	ds_read_b128 v[14:17], v219 offset:17152
	s_waitcnt lgkmcnt(4)
	v_mfma_f32_16x16x32_bf16 v[94:97], v[18:21], v[130:133], v[94:97]
	v_mfma_f32_16x16x32_bf16 v[90:93], v[22:25], v[130:133], v[90:93]
	v_mfma_f32_16x16x32_bf16 v[94:97], v[26:29], v[62:65], v[94:97]
	v_mfma_f32_16x16x32_bf16 v[90:93], v[30:33], v[62:65], v[90:93]
	s_cmp_eq_u32 s73, 0
	s_cbranch_scc1 .Lrg_k_A_nd9
	s_add_i32 m0, s59, 0
	v_add_co_u32_e32 v222, vcc, s75, v220
	s_nop 1
	v_addc_co_u32_e32 v223, vcc, 0, v221, vcc
	global_load_lds_dwordx4 v[222:223], off
; #define ATT_KLOAD(buf, p) do { const bf16_t* kp_ = kloc + (size_t)((p) * 8 * NH) * 1024; \
;         _Pragma("unroll") for (int f = 0; f < 2; ++f) _Pragma("unroll") for (int ks = 0; ks < 4; ++ks) ka[buf][f * 4 + ks] = *(const bf16x8*)(kp_ + f * 128 + ks * 256); } while (0)
; template <bool LOCAL>
; __device__ __forceinline__ void attn_unit(const bf16_t* Q, const bf16_t* KT, const bf16_t* VT, bf16_t* O, LAS unsigned char* lds, int b, int h, int r, int w, int tq, int lane) {
;     ...
;     if (LOCAL) {
;         const bf16_t* kloc = KT + ((size_t)(((rgl >> 3) + (q >> 2)) * NH + h)) * 1024 + (q & 3) * 32 + g * 8;
;         bf16x8 ka[2][8];
;     ...
;         ATT_KLOAD(0, 0);
; #pragma unroll
;         for (int p = 0; p < 8; ++p) {
;             __builtin_amdgcn_s_barrier();
;             if (p + 1 < 8) ATT_KLOAD((p + 1) & 1, p + 1);
;             __builtin_amdgcn_sched_barrier(0);
; #pragma unroll
;             for (int f = 0; f < 2; ++f) { f32x4 a = {0.f, 0.f, 0.f, 0.f};
; #pragma unroll
;                 for (int ks = 0; ks < 4; ++ks) a = __builtin_amdgcn_mfma_f32_16x16x32_bf16(ka[p & 1][f * 4 + ks], bq[ks], a, 0, 0, 0);
;                 s[2 * p + f] = a; }
;             __builtin_amdgcn_sched_barrier(0);
;         }
;     ...
;     }
.Lrg_k_A_nd9:
	s_waitcnt vmcnt(4)
	s_barrier
	ds_read_b128 v[18:21], v219 offset:24576
	ds_read_b128 v[22:25], v219 offset:24832
	ds_read_b128 v[26:29], v219 offset:25088
	ds_read_b128 v[30:33], v219 offset:25344
	s_waitcnt lgkmcnt(4)
	v_mfma_f32_16x16x32_bf16 v[86:89], v[2:5], v[138:141], 0
	v_mfma_f32_16x16x32_bf16 v[82:85], v[6:9], v[138:141], 0
	v_mfma_f32_16x16x32_bf16 v[86:89], v[10:13], v[134:137], v[86:89]
	v_mfma_f32_16x16x32_bf16 v[82:85], v[14:17], v[134:137], v[82:85]
	s_cmp_eq_u32 s73, 0
	s_cbranch_scc1 .Lrg_k_A_nd10
	s_add_i32 m0, s59, 8192
	v_add_co_u32_e32 v222, vcc, s75, v226
	s_nop 1
	v_addc_co_u32_e32 v223, vcc, 0, v227, vcc
	global_load_lds_dwordx4 v[222:223], off
.Lrg_k_A_nd10:
	s_waitcnt vmcnt(3)
	s_barrier
	ds_read_b128 v[2:5], v219 offset:32768
	ds_read_b128 v[6:9], v219 offset:33024
	ds_read_b128 v[10:13], v219 offset:33280
	ds_read_b128 v[14:17], v219 offset:33536
	s_waitcnt lgkmcnt(4)
	v_mfma_f32_16x16x32_bf16 v[86:89], v[18:21], v[130:133], v[86:89]
	v_mfma_f32_16x16x32_bf16 v[82:85], v[22:25], v[130:133], v[82:85]
	v_mfma_f32_16x16x32_bf16 v[86:89], v[26:29], v[62:65], v[86:89]
	v_mfma_f32_16x16x32_bf16 v[82:85], v[30:33], v[62:65], v[82:85]
	s_waitcnt vmcnt(2)
	s_barrier
	ds_read_b128 v[18:21], v219 offset:40960
	ds_read_b128 v[22:25], v219 offset:41216
	ds_read_b128 v[26:29], v219 offset:41472
	ds_read_b128 v[30:33], v219 offset:41728
	s_waitcnt lgkmcnt(4)
	v_mfma_f32_16x16x32_bf16 v[78:81], v[2:5], v[138:141], 0
	v_mfma_f32_16x16x32_bf16 v[74:77], v[6:9], v[138:141], 0
	v_mfma_f32_16x16x32_bf16 v[78:81], v[10:13], v[134:137], v[78:81]
	v_mfma_f32_16x16x32_bf16 v[74:77], v[14:17], v[134:137], v[74:77]
	s_waitcnt vmcnt(1)
	s_barrier
	ds_read_b128 v[2:5], v219 offset:49152
	ds_read_b128 v[6:9], v219 offset:49408
	ds_read_b128 v[10:13], v219 offset:49664
	ds_read_b128 v[14:17], v219 offset:49920
	s_waitcnt lgkmcnt(4)
	v_mfma_f32_16x16x32_bf16 v[78:81], v[18:21], v[130:133], v[78:81]
	v_mfma_f32_16x16x32_bf16 v[74:77], v[22:25], v[130:133], v[74:77]
	v_mfma_f32_16x16x32_bf16 v[78:81], v[26:29], v[62:65], v[78:81]
	v_mfma_f32_16x16x32_bf16 v[74:77], v[30:33], v[62:65], v[74:77]
	s_waitcnt vmcnt(0)
	s_barrier
	ds_read_b128 v[18:21], v219 offset:57344
	ds_read_b128 v[22:25], v219 offset:57600
	ds_read_b128 v[26:29], v219 offset:57856
	ds_read_b128 v[30:33], v219 offset:58112
	s_waitcnt lgkmcnt(4)
	v_mfma_f32_16x16x32_bf16 v[70:73], v[2:5], v[138:141], 0
	v_mfma_f32_16x16x32_bf16 v[66:69], v[6:9], v[138:141], 0
	v_mfma_f32_16x16x32_bf16 v[70:73], v[10:13], v[134:137], v[70:73]
	v_mfma_f32_16x16x32_bf16 v[66:69], v[14:17], v[134:137], v[66:69]
	s_waitcnt vmcnt(1)
	s_barrier
	s_waitcnt lgkmcnt(0)
	v_mfma_f32_16x16x32_bf16 v[70:73], v[18:21], v[130:133], v[70:73]
	v_mfma_f32_16x16x32_bf16 v[66:69], v[22:25], v[130:133], v[66:69]
	v_mfma_f32_16x16x32_bf16 v[70:73], v[26:29], v[62:65], v[70:73]
	v_mfma_f32_16x16x32_bf16 v[66:69], v[30:33], v[62:65], v[66:69]
	s_cmp_eq_u32 s73, 0
	s_cbranch_scc1 .Lrg_k_A_end
	s_waitcnt vmcnt(0)
	s_barrier

; #define ATT_KLOAD(buf, p) do { const bf16_t* kp_ = kloc + (size_t)((p) * 8 * NH) * 1024; \
;         _Pragma("unroll") for (int f = 0; f < 2; ++f) _Pragma("unroll") for (int ks = 0; ks < 4; ++ks) ka[buf][f * 4 + ks] = *(const bf16x8*)(kp_ + f * 128 + ks * 256); } while (0)
; template <bool LOCAL>
; __device__ __forceinline__ void attn_unit(const bf16_t* Q, const bf16_t* KT, const bf16_t* VT, bf16_t* O, LAS unsigned char* lds, int b, int h, int r, int w, int tq, int lane) {
;     ...
;     if (LOCAL) {
;         const bf16_t* kloc = KT + ((size_t)(((rgl >> 3) + (q >> 2)) * NH + h)) * 1024 + (q & 3) * 32 + g * 8;
;         bf16x8 ka[2][8];
;     ...
;         ATT_KLOAD(0, 0);
; #pragma unroll
;         for (int p = 0; p < 8; ++p) {
;             __builtin_amdgcn_s_barrier();
;             if (p + 1 < 8) ATT_KLOAD((p + 1) & 1, p + 1);
;             __builtin_amdgcn_sched_barrier(0);
; #pragma unroll
;             for (int f = 0; f < 2; ++f) { f32x4 a = {0.f, 0.f, 0.f, 0.f};
; #pragma unroll
;                 for (int ks = 0; ks < 4; ++ks) a = __builtin_amdgcn_mfma_f32_16x16x32_bf16(ka[p & 1][f * 4 + ks], bq[ks], a, 0, 0, 0);
;                 s[2 * p + f] = a; }
;             __builtin_amdgcn_sched_barrier(0);
;         }
;     ...
;     }
.Lrg_k_B:
	s_waitcnt vmcnt(6)
	s_barrier
	s_waitcnt vmcnt(5)
	s_barrier
	s_add_i32 m0, s59, 57344
	v_add_co_u32_e32 v222, vcc, s2, v226
	s_nop 1
	v_addc_co_u32_e32 v223, vcc, 0, v227, vcc
	global_load_lds_dwordx4 v[222:223], off
	s_waitcnt vmcnt(5)
	s_barrier
	ds_read_b128 v[2:5], v219 offset:16384
	ds_read_b128 v[6:9], v219 offset:16640
	ds_read_b128 v[10:13], v219 offset:16896
	ds_read_b128 v[14:17], v219 offset:17152
	s_add_i32 m0, s59, 0
	v_add_co_u32_e32 v222, vcc, s60, v220
	s_nop 1
	v_addc_co_u32_e32 v223, vcc, 0, v221, vcc
	global_load_lds_dwordx4 v[222:223], off
	s_waitcnt vmcnt(5)
	s_barrier
	ds_read_b128 v[18:21], v219 offset:24576
	ds_read_b128 v[22:25], v219 offset:24832
	ds_read_b128 v[26:29], v219 offset:25088
	ds_read_b128 v[30:33], v219 offset:25344
	s_waitcnt lgkmcnt(4)
	v_mfma_f32_16x16x32_bf16 v[126:129], v[2:5], v[138:141], 0
	v_mfma_f32_16x16x32_bf16 v[122:125], v[6:9], v[138:141], 0
	v_mfma_f32_16x16x32_bf16 v[126:129], v[10:13], v[134:137], v[126:129]
	v_mfma_f32_16x16x32_bf16 v[122:125], v[14:17], v[134:137], v[122:125]
	s_add_i32 m0, s59, 8192
	v_add_co_u32_e32 v222, vcc, s60, v226
	s_nop 1
	v_addc_co_u32_e32 v223, vcc, 0, v227, vcc
	global_load_lds_dwordx4 v[222:223], off
	s_waitcnt vmcnt(5)
	s_barrier
	ds_read_b128 v[2:5], v219 offset:32768
	ds_read_b128 v[6:9], v219 offset:33024
	ds_read_b128 v[10:13], v219 offset:33280
	ds_read_b128 v[14:17], v219 offset:33536
	s_waitcnt lgkmcnt(4)
	v_mfma_f32_16x16x32_bf16 v[126:129], v[18:21], v[130:133], v[126:129]
	v_mfma_f32_16x16x32_bf16 v[122:125], v[22:25], v[130:133], v[122:125]
	v_mfma_f32_16x16x32_bf16 v[126:129], v[26:29], v[62:65], v[126:129]
	v_mfma_f32_16x16x32_bf16 v[122:125], v[30:33], v[62:65], v[122:125]
	s_add_i32 m0, s59, 16384
	v_add_co_u32_e32 v222, vcc, s61, v220
	s_nop 1
	v_addc_co_u32_e32 v223, vcc, 0, v221, vcc
	global_load_lds_dwordx4 v[222:223], off
	s_waitcnt vmcnt(5)
	s_barrier
	ds_read_b128 v[18:21], v219 offset:40960
	ds_read_b128 v[22:25], v219 offset:41216
	ds_read_b128 v[26:29], v219 offset:41472
	ds_read_b128 v[30:33], v219 offset:41728
	s_waitcnt lgkmcnt(4)
	v_mfma_f32_16x16x32_bf16 v[118:121], v[2:5], v[138:141], 0
	v_mfma_f32_16x16x32_bf16 v[114:117], v[6:9], v[138:141], 0
	v_mfma_f32_16x16x32_bf16 v[118:121], v[10:13], v[134:137], v[118:121]
	v_mfma_f32_16x16x32_bf16 v[114:117], v[14:17], v[134:137], v[114:117]
	s_add_i32 m0, s59, 24576
	v_add_co_u32_e32 v222, vcc, s61, v226
	s_nop 1
	v_addc_co_u32_e32 v223, vcc, 0, v227, vcc
	global_load_lds_dwordx4 v[222:223], off
	s_waitcnt vmcnt(5)
	s_barrier
	ds_read_b128 v[2:5], v219 offset:49152
	ds_read_b128 v[6:9], v219 offset:49408
	ds_read_b128 v[10:13], v219 offset:49664
	ds_read_b128 v[14:17], v219 offset:49920
	s_waitcnt lgkmcnt(4)
	v_mfma_f32_16x16x32_bf16 v[118:121], v[18:21], v[130:133], v[118:121]
	v_mfma_f32_16x16x32_bf16 v[114:117], v[22:25], v[130:133], v[114:117]
	v_mfma_f32_16x16x32_bf16 v[118:121], v[26:29], v[62:65], v[118:121]
	v_mfma_f32_16x16x32_bf16 v[114:117], v[30:33], v[62:65], v[114:117]
	s_add_i32 m0, s59, 32768
	v_add_co_u32_e32 v222, vcc, s17, v220
	s_nop 1
	v_addc_co_u32_e32 v223, vcc, 0, v221, vcc
	global_load_lds_dwordx4 v[222:223], off
	s_waitcnt vmcnt(5)
	s_barrier
	ds_read_b128 v[18:21], v219 offset:57344
	ds_read_b128 v[22:25], v219 offset:57600
	ds_read_b128 v[26:29], v219 offset:57856
	ds_read_b128 v[30:33], v219 offset:58112
	s_waitcnt lgkmcnt(4)
	v_mfma_f32_16x16x32_bf16 v[110:113], v[2:5], v[138:141], 0
	v_mfma_f32_16x16x32_bf16 v[106:109], v[6:9], v[138:141], 0
	v_mfma_f32_16x16x32_bf16 v[110:113], v[10:13], v[134:137], v[110:113]
	v_mfma_f32_16x16x32_bf16 v[106:109], v[14:17], v[134:137], v[106:109]
	s_add_i32 m0, s59, 40960
	v_add_co_u32_e32 v222, vcc, s17, v226
	s_nop 1
	v_addc_co_u32_e32 v223, vcc, 0, v227, vcc
	global_load_lds_dwordx4 v[222:223], off
	s_waitcnt vmcnt(5)
	s_barrier
	ds_read_b128 v[2:5], v219 offset:0
	ds_read_b128 v[6:9], v219 offset:256
	ds_read_b128 v[10:13], v219 offset:512
	ds_read_b128 v[14:17], v219 offset:768
	s_waitcnt lgkmcnt(4)
	v_mfma_f32_16x16x32_bf16 v[110:113], v[18:21], v[130:133], v[110:113]
	v_mfma_f32_16x16x32_bf16 v[106:109], v[22:25], v[130:133], v[106:109]
	v_mfma_f32_16x16x32_bf16 v[110:113], v[26:29], v[62:65], v[110:113]
	v_mfma_f32_16x16x32_bf16 v[106:109], v[30:33], v[62:65], v[106:109]
	s_add_i32 m0, s59, 49152
	v_add_co_u32_e32 v222, vcc, s62, v220
	s_nop 1
	v_addc_co_u32_e32 v223, vcc, 0, v221, vcc
	global_load_lds_dwordx4 v[222:223], off
	s_waitcnt vmcnt(5)
	s_barrier
	ds_read_b128 v[18:21], v219 offset:8192
	ds_read_b128 v[22:25], v219 offset:8448
	ds_read_b128 v[26:29], v219 offset:8704
	ds_read_b128 v[30:33], v219 offset:8960
	s_waitcnt lgkmcnt(4)
	v_mfma_f32_16x16x32_bf16 v[102:105], v[2:5], v[138:141], 0
	v_mfma_f32_16x16x32_bf16 v[98:101], v[6:9], v[138:141], 0
	v_mfma_f32_16x16x32_bf16 v[102:105], v[10:13], v[134:137], v[102:105]
	v_mfma_f32_16x16x32_bf16 v[98:101], v[14:17], v[134:137], v[98:101]
	s_add_i32 m0, s59, 57344
	v_add_co_u32_e32 v222, vcc, s62, v226
	s_nop 1
	v_addc_co_u32_e32 v223, vcc, 0, v227, vcc
	global_load_lds_dwordx4 v[222:223], off
	s_waitcnt vmcnt(5)
	s_barrier
	ds_read_b128 v[2:5], v219 offset:16384
	ds_read_b128 v[6:9], v219 offset:16640
	ds_read_b128 v[10:13], v219 offset:16896
	ds_read_b128 v[14:17], v219 offset:17152
	s_waitcnt lgkmcnt(4)
	v_mfma_f32_16x16x32_bf16 v[102:105], v[18:21], v[130:133], v[102:105]
	v_mfma_f32_16x16x32_bf16 v[98:101], v[22:25], v[130:133], v[98:101]
	v_mfma_f32_16x16x32_bf16 v[102:105], v[26:29], v[62:65], v[102:105]
	v_mfma_f32_16x16x32_bf16 v[98:101], v[30:33], v[62:65], v[98:101]
	s_cmp_eq_u32 s73, 0
	s_cbranch_scc1 .Lrg_k_B_nd9
	s_add_i32 m0, s59, 0
	v_add_co_u32_e32 v222, vcc, s75, v220
	s_nop 1
	v_addc_co_u32_e32 v223, vcc, 0, v221, vcc
	global_load_lds_dwordx4 v[222:223], off
; #define ATT_KLOAD(buf, p) do { const bf16_t* kp_ = kloc + (size_t)((p) * 8 * NH) * 1024; \
;         _Pragma("unroll") for (int f = 0; f < 2; ++f) _Pragma("unroll") for (int ks = 0; ks < 4; ++ks) ka[buf][f * 4 + ks] = *(const bf16x8*)(kp_ + f * 128 + ks * 256); } while (0)
; template <bool LOCAL>
; __device__ __forceinline__ void attn_unit(const bf16_t* Q, const bf16_t* KT, const bf16_t* VT, bf16_t* O, LAS unsigned char* lds, int b, int h, int r, int w, int tq, int lane) {
;     ...
;     if (LOCAL) {
;         const bf16_t* kloc = KT + ((size_t)(((rgl >> 3) + (q >> 2)) * NH + h)) * 1024 + (q & 3) * 32 + g * 8;
;         bf16x8 ka[2][8];
;     ...
;         ATT_KLOAD(0, 0);
; #pragma unroll
;         for (int p = 0; p < 8; ++p) {
;             __builtin_amdgcn_s_barrier();
;             if (p + 1 < 8) ATT_KLOAD((p + 1) & 1, p + 1);
;             __builtin_amdgcn_sched_barrier(0);
; #pragma unroll
;             for (int f = 0; f < 2; ++f) { f32x4 a = {0.f, 0.f, 0.f, 0.f};
; #pragma unroll
;                 for (int ks = 0; ks < 4; ++ks) a = __builtin_amdgcn_mfma_f32_16x16x32_bf16(ka[p & 1][f * 4 + ks], bq[ks], a, 0, 0, 0);
;                 s[2 * p + f] = a; }
;             __builtin_amdgcn_sched_barrier(0);
;         }
;     ...
;     }
.Lrg_k_B_nd9:
	s_waitcnt vmcnt(4)
	s_barrier
	ds_read_b128 v[18:21], v219 offset:24576
	ds_read_b128 v[22:25], v219 offset:24832
	ds_read_b128 v[26:29], v219 offset:25088
	ds_read_b128 v[30:33], v219 offset:25344
	s_waitcnt lgkmcnt(4)
	v_mfma_f32_16x16x32_bf16 v[94:97], v[2:5], v[138:141], 0
	v_mfma_f32_16x16x32_bf16 v[90:93], v[6:9], v[138:141], 0
	v_mfma_f32_16x16x32_bf16 v[94:97], v[10:13], v[134:137], v[94:97]
	v_mfma_f32_16x16x32_bf16 v[90:93], v[14:17], v[134:137], v[90:93]
	s_cmp_eq_u32 s73, 0
	s_cbranch_scc1 .Lrg_k_B_nd10
	s_add_i32 m0, s59, 8192
	v_add_co_u32_e32 v222, vcc, s75, v226
	s_nop 1
	v_addc_co_u32_e32 v223, vcc, 0, v227, vcc
	global_load_lds_dwordx4 v[222:223], off
.Lrg_k_B_nd10:
	s_waitcnt vmcnt(3)
	s_barrier
	ds_read_b128 v[2:5], v219 offset:32768
	ds_read_b128 v[6:9], v219 offset:33024
	ds_read_b128 v[10:13], v219 offset:33280
	ds_read_b128 v[14:17], v219 offset:33536
	s_waitcnt lgkmcnt(4)
	v_mfma_f32_16x16x32_bf16 v[94:97], v[18:21], v[130:133], v[94:97]
	v_mfma_f32_16x16x32_bf16 v[90:93], v[22:25], v[130:133], v[90:93]
	v_mfma_f32_16x16x32_bf16 v[94:97], v[26:29], v[62:65], v[94:97]
	v_mfma_f32_16x16x32_bf16 v[90:93], v[30:33], v[62:65], v[90:93]
	s_waitcnt vmcnt(2)
	s_barrier
	ds_read_b128 v[18:21], v219 offset:40960
	ds_read_b128 v[22:25], v219 offset:41216
	ds_read_b128 v[26:29], v219 offset:41472
	ds_read_b128 v[30:33], v219 offset:41728
	s_waitcnt lgkmcnt(4)
	v_mfma_f32_16x16x32_bf16 v[86:89], v[2:5], v[138:141], 0
	v_mfma_f32_16x16x32_bf16 v[82:85], v[6:9], v[138:141], 0
	v_mfma_f32_16x16x32_bf16 v[86:89], v[10:13], v[134:137], v[86:89]
	v_mfma_f32_16x16x32_bf16 v[82:85], v[14:17], v[134:137], v[82:85]
	s_waitcnt vmcnt(1)
	s_barrier
	ds_read_b128 v[2:5], v219 offset:49152
	ds_read_b128 v[6:9], v219 offset:49408
	ds_read_b128 v[10:13], v219 offset:49664
	ds_read_b128 v[14:17], v219 offset:49920
	s_waitcnt lgkmcnt(4)
	v_mfma_f32_16x16x32_bf16 v[86:89], v[18:21], v[130:133], v[86:89]
	v_mfma_f32_16x16x32_bf16 v[82:85], v[22:25], v[130:133], v[82:85]
	v_mfma_f32_16x16x32_bf16 v[86:89], v[26:29], v[62:65], v[86:89]
	v_mfma_f32_16x16x32_bf16 v[82:85], v[30:33], v[62:65], v[82:85]
	s_waitcnt vmcnt(0)
	s_barrier
	ds_read_b128 v[18:21], v219 offset:57344
	ds_read_b128 v[22:25], v219 offset:57600
	ds_read_b128 v[26:29], v219 offset:57856
	ds_read_b128 v[30:33], v219 offset:58112
	s_waitcnt lgkmcnt(4)
	v_mfma_f32_16x16x32_bf16 v[78:81], v[2:5], v[138:141], 0
	v_mfma_f32_16x16x32_bf16 v[74:77], v[6:9], v[138:141], 0
	v_mfma_f32_16x16x32_bf16 v[78:81], v[10:13], v[134:137], v[78:81]
	v_mfma_f32_16x16x32_bf16 v[74:77], v[14:17], v[134:137], v[74:77]
	s_waitcnt vmcnt(1)
	s_barrier
	ds_read_b128 v[2:5], v219 offset:0
	ds_read_b128 v[6:9], v219 offset:256
	ds_read_b128 v[10:13], v219 offset:512
	ds_read_b128 v[14:17], v219 offset:768
	s_waitcnt lgkmcnt(4)
	v_mfma_f32_16x16x32_bf16 v[78:81], v[18:21], v[130:133], v[78:81]
	v_mfma_f32_16x16x32_bf16 v[74:77], v[22:25], v[130:133], v[74:77]
	v_mfma_f32_16x16x32_bf16 v[78:81], v[26:29], v[62:65], v[78:81]
	v_mfma_f32_16x16x32_bf16 v[74:77], v[30:33], v[62:65], v[74:77]
	s_cmp_eq_u32 s73, 0
	s_cbranch_scc1 .Lrg_k_B_end
	s_waitcnt vmcnt(0)
	s_barrier
	ds_read_b128 v[18:21], v219 offset:8192
	ds_read_b128 v[22:25], v219 offset:8448
	ds_read_b128 v[26:29], v219 offset:8704
	ds_read_b128 v[30:33], v219 offset:8960
	s_waitcnt lgkmcnt(4)
	v_mfma_f32_16x16x32_bf16 v[70:73], v[2:5], v[138:141], 0
	v_mfma_f32_16x16x32_bf16 v[66:69], v[6:9], v[138:141], 0
	v_mfma_f32_16x16x32_bf16 v[70:73], v[10:13], v[134:137], v[70:73]
	v_mfma_f32_16x16x32_bf16 v[66:69], v[14:17], v[134:137], v[66:69]
	s_waitcnt lgkmcnt(0)
	v_mfma_f32_16x16x32_bf16 v[70:73], v[18:21], v[130:133], v[70:73]
	v_mfma_f32_16x16x32_bf16 v[66:69], v[22:25], v[130:133], v[66:69]
	v_mfma_f32_16x16x32_bf16 v[70:73], v[26:29], v[62:65], v[70:73]
	v_mfma_f32_16x16x32_bf16 v[66:69], v[30:33], v[62:65], v[66:69]
